# P0 ada GEMV: pre-pass converts c to bf16 MFMA-tiled copy in workspace (write-through stores + counter, polled by wave 0 of each workgroup); K loop fully unrolled, one contiguous 1 KB load per c tile (
# speedup vs baseline: 1.0638x; 1.0055x over previous
.LBB0_5:
	s_or_b64 exec, exec, s[4:5]
	s_add_u32 s14, s70, 0x16000000
	s_addc_u32 s15, s71, 0
	s_lshl_b32 s0, s2, 3
	s_lshr_b32 s1, s35, 6
	s_lshl_b32 s34, s96, 3
	s_add_i32 s68, s1, s0
	s_add_u32 s76, s70, 0x800000
	s_addc_u32 s77, s71, 0
	s_add_u32 s78, s70, 0x2800000
	s_addc_u32 s79, s71, 0
	s_add_u32 s0, s70, 0x4800000
	v_writelane_b32 v255, s1, 5
	s_addc_u32 s1, s71, 0
	s_add_u32 s80, s70, 0x6800000
	s_addc_u32 s81, s71, 0
	s_add_u32 s92, s70, 0x7000000
	s_addc_u32 s72, s71, 0
	s_add_u32 s82, s70, 0x7400000
	s_addc_u32 s83, s71, 0
	v_writelane_b32 v255, s0, 6
	v_readlane_b32 s0, v255, 5
	s_lshl_b32 s3, s0, 8
	s_add_i32 s3, s3, s2
	s_cmp_gt_u32 s3, 575
	s_cbranch_scc1 .Lpc_skip
	s_mul_i32 s4, s3, 0x1c72
	s_lshr_b32 s4, s4, 16
	s_mul_i32 s5, s4, 9
	s_sub_i32 s5, s3, s5
	v_and_b32_e32 v1, 63, v0
	v_and_b32_e32 v2, 15, v1
	v_lshrrev_b32_e32 v3, 4, v1
	s_lshl_b32 s6, s5, 4
	s_sub_i32 s6, s6, 4
	v_add_u32_e32 v4, s6, v2
	v_min_i32_e32 v4, 0x7f, v4
	v_cmp_gt_i32_e32 vcc, 0, v4
	v_max_i32_e32 v5, 0, v4
	v_lshlrev_b32_e32 v5, 13, v5
	v_lshlrev_b32_e32 v6, 13, v2
	s_lshl_b32 s7, s4, 7
	v_lshl_add_u32 v7, v3, 5, s7
	v_add_u32_e32 v5, v5, v7
	v_add_u32_e32 v6, v6, v7
	v_mov_b32_e32 v8, s62
	v_mov_b32_e32 v9, s63
	v_mov_b32_e32 v10, s60
	v_mov_b32_e32 v11, s61
	v_mov_b32_e32 v13, 0
	v_cndmask_b32_e32 v12, v5, v6, vcc
	v_cndmask_b32_e32 v8, v8, v10, vcc
	v_cndmask_b32_e32 v9, v9, v11, vcc
	s_nop 0
	v_lshl_add_u64 v[8:9], v[8:9], 0, v[12:13]
	global_load_dwordx4 v[16:19], v[8:9], off
	global_load_dwordx4 v[20:23], v[8:9], off offset:16
	s_lshl_b32 s4, s3, 10
	v_lshl_add_u32 v14, v1, 4, s4
	s_add_u32 s4, s70, 0x7800000
	s_addc_u32 s5, s71, 0
	s_waitcnt vmcnt(0)
	v_cvt_pk_bf16_f32 v24, v16, v17
	v_cvt_pk_bf16_f32 v25, v18, v19
	v_cvt_pk_bf16_f32 v26, v20, v21
	v_cvt_pk_bf16_f32 v27, v22, v23
	global_store_dwordx4 v14, v[24:27], s[4:5] sc0 sc1
	v_mov_b32_e32 v15, 1
	v_mov_b32_e32 v14, 0x3f00
	s_waitcnt vmcnt(0)
	s_mov_b64 s[6:7], exec
	s_mov_b64 exec, 1
	global_atomic_add v14, v15, s[70:71]
	s_mov_b64 exec, s[6:7]
.Lpc_skip:
	s_bitcmp1_b32 s2, 0
	v_and_b32_e32 v170, 63, v0
	v_writelane_b32 v255, s1, 7
	s_cselect_b64 s[0:1], -1, 0
	s_mov_b64 s[4:5], -1
	s_and_b64 vcc, exec, s[0:1]
	v_writelane_b32 v255, s92, 8
	s_cbranch_vccz .LBB0_76
	s_cmpk_gt_i32 s68, 0x2fff
	s_cbranch_scc1 .LBB0_25
	v_readlane_b32 s0, v255, 5
	s_lshl_b32 s0, s0, 14
	v_lshlrev_b32_e32 v2, 4, v0
	s_add_i32 s0, s0, 0
	v_lshrrev_b32_e32 v1, 3, v170
	v_and_b32_e32 v22, 0x70, v2
	v_lshlrev_b32_e32 v2, 3, v0
	v_add_u32_e32 v28, s0, v22
	v_mul_u32_u24_e32 v29, 0x84, v1
	v_and_b32_e32 v2, 56, v2
	v_mov_b32_e32 v3, 0
	v_readlane_b32 s6, v255, 6
	v_mul_u32_u24_e32 v6, 0x84, v2
	v_lshlrev_b32_e32 v2, 1, v2
	v_readlane_b32 s7, v255, 7
	v_lshlrev_b32_e32 v7, 2, v1
	v_mov_b32_e32 v23, v3
	v_add_u32_e32 v28, v28, v29
	s_mov_b32 s5, 0
	v_or_b32_e32 v24, 8, v1
	v_or_b32_e32 v25, 16, v1
	v_or_b32_e32 v26, 24, v1
	v_lshl_add_u64 v[4:5], s[6:7], 0, v[2:3]
	v_add3_u32 v27, s0, v6, v7
	v_lshl_add_u64 v[6:7], s[78:79], 0, v[2:3]
	v_lshl_add_u64 v[8:9], s[82:83], 0, v[2:3]
	v_lshl_add_u64 v[10:11], s[80:81], 0, v[2:3]
	v_lshl_add_u64 v[12:13], s[76:77], 0, v[2:3]
	v_lshl_add_u64 v[14:15], s[22:23], 0, v[22:23]
	v_lshl_add_u64 v[16:17], s[18:19], 0, v[22:23]
	v_lshl_add_u64 v[18:19], s[46:47], 0, v[22:23]
	v_lshl_add_u64 v[20:21], s[48:49], 0, v[22:23]
	v_lshl_add_u64 v[22:23], s[36:37], 0, v[22:23]
	v_add_u32_e32 v29, 0x420, v28
	v_add_u32_e32 v30, 0x428, v28
	v_add_u32_e32 v31, 0x840, v28
	v_add_u32_e32 v32, 0x848, v28
	v_add_u32_e32 v33, 0xc60, v28
	v_add_u32_e32 v34, 0xc68, v28
	v_add_u32_e32 v35, 0x1080, v28
	v_add_u32_e32 v36, 0x1088, v28
	v_add_u32_e32 v37, 0x14a0, v28
	v_add_u32_e32 v38, 0x14a8, v28
	v_add_u32_e32 v39, 0x18c0, v28
	v_add_u32_e32 v40, 0x18c8, v28
	v_add_u32_e32 v41, 0x1ce0, v28
	v_add_u32_e32 v42, 0x1ce8, v28
	s_movk_i32 s0, 0x7fff
	s_mov_b32 s1, 0xffff0000
	s_mov_b32 s3, 0x40000
	s_mov_b32 s8, s68
	s_branch .LBB0_9

.LBB0_30:
	v_add_u32_e32 v130, s93, v137
	v_mad_u64_u32 v[236:237], s[0:1], v130, s69, v[226:227]
	global_load_dwordx3 v[166:168], v[236:237], off nt
	v_add_u32_e32 v132, 1, v130
	v_mad_u64_u32 v[236:237], s[0:1], v132, s69, v[226:227]
	global_load_dwordx3 v[184:186], v[236:237], off nt
	v_add_u32_e32 v132, 2, v130
	v_mad_u64_u32 v[236:237], s[0:1], v132, s69, v[226:227]
	global_load_dwordx3 v[188:190], v[236:237], off nt
	v_add_u32_e32 v132, 3, v130
	v_mad_u64_u32 v[236:237], s[0:1], v132, s69, v[226:227]
	global_load_dwordx3 v[192:194], v[236:237], off nt
	v_add_u32_e32 v132, 4, v130
	v_mad_u64_u32 v[236:237], s[0:1], v132, s69, v[226:227]
	global_load_dwordx3 v[214:216], v[236:237], off nt
	v_add_u32_e32 v132, 5, v130
	v_mad_u64_u32 v[236:237], s[0:1], v132, s69, v[226:227]
	global_load_dwordx3 v[218:220], v[236:237], off nt
	v_add_u32_e32 v132, 6, v130
	v_mad_u64_u32 v[236:237], s[0:1], v132, s69, v[226:227]
	global_load_dwordx3 v[228:230], v[236:237], off nt
	v_add_u32_e32 v132, 7, v130
	v_mad_u64_u32 v[236:237], s[0:1], v132, s69, v[226:227]
	global_load_dwordx3 v[232:234], v[236:237], off nt
	v_readlane_b32 s74, v255, 5
	s_mul_i32 s73, s74, 0x12000
	s_add_u32 s32, s70, 0x7800000
	s_addc_u32 s33, s71, 0
	s_add_u32 s32, s32, s73
	s_addc_u32 s33, s33, 0
	v_lshlrev_b32_e32 v134, 4, v170
	s_cmp_lg_u32 s74, 0
	s_cbranch_scc1 .Lp0cb_odd_sync
	v_mov_b32_e32 v136, 0x3f00
	s_mov_b32 s73, 0
.Lp0cb_odd_poll:
	global_load_dword v132, v136, s[70:71] sc1
	s_add_i32 s73, s73, 1
	s_waitcnt vmcnt(0)
	v_readfirstlane_b32 s74, v132
	s_cmp_ge_u32 s74, 576
	s_cbranch_scc1 .Lp0cb_odd_ok
	s_sleep 1
	s_cmp_lt_u32 s73, 0x8000
	s_cbranch_scc1 .Lp0cb_odd_poll

.Lp0cb_odd_sync:
	s_barrier
	global_load_dwordx4 v[122:125], v134, s[32:33]
	s_add_u32 s32, s32, 0x400
	s_addc_u32 s33, s33, 0
	global_load_dwordx4 v[126:129], v134, s[32:33]
	s_add_u32 s32, s32, 0x400
	s_addc_u32 s33, s33, 0
	global_load_dwordx4 v[138:141], v134, s[32:33]
	s_add_u32 s32, s32, 0x400
	s_addc_u32 s33, s33, 0
	global_load_dwordx4 v[142:145], v134, s[32:33]
	s_add_u32 s32, s32, 0x400
	s_addc_u32 s33, s33, 0
	global_load_dwordx4 v[146:149], v134, s[32:33]
	s_add_u32 s32, s32, 0x400
	s_addc_u32 s33, s33, 0
	global_load_dwordx4 v[150:153], v134, s[32:33]
	s_add_u32 s32, s32, 0x400
	s_addc_u32 s33, s33, 0
	global_load_dwordx4 v[154:157], v134, s[32:33]
	s_add_u32 s32, s32, 0x400
	s_addc_u32 s33, s33, 0
	global_load_dwordx4 v[158:161], v134, s[32:33]
	s_add_u32 s32, s32, 0x400
	s_addc_u32 s33, s33, 0
	global_load_dwordx4 v[162:165], v134, s[32:33]
	s_add_u32 s32, s32, 0x400
	s_addc_u32 s33, s33, 0
	global_load_dwordx4 v[172:175], v134, s[32:33]
	s_add_u32 s32, s32, 0x400
	s_addc_u32 s33, s33, 0
	global_load_dwordx4 v[176:179], v134, s[32:33]
	s_add_u32 s32, s32, 0x400
	s_addc_u32 s33, s33, 0
	global_load_dwordx4 v[180:183], v134, s[32:33]
	s_add_i32 s93, s93, 256
	s_waitcnt vmcnt(12)
	v_cvt_pk_bf16_f32 v110, v166, v184
	v_cvt_pk_bf16_f32 v111, v188, v192
	v_cvt_pk_bf16_f32 v112, v214, v218
	v_cvt_pk_bf16_f32 v113, v228, v232
	v_cvt_pk_bf16_f32 v114, v167, v185
	v_cvt_pk_bf16_f32 v115, v189, v193
	v_cvt_pk_bf16_f32 v116, v215, v219
	v_cvt_pk_bf16_f32 v117, v229, v233
	v_cvt_pk_bf16_f32 v118, v168, v186
	v_cvt_pk_bf16_f32 v119, v190, v194
	v_cvt_pk_bf16_f32 v120, v216, v220
	v_cvt_pk_bf16_f32 v121, v230, v234
	v_add_u32_e32 v132, 32, v130
	v_mad_u64_u32 v[236:237], s[0:1], v132, s69, v[226:227]
	global_load_dwordx3 v[166:168], v[236:237], off nt
	v_add_u32_e32 v132, 33, v130
	v_mad_u64_u32 v[236:237], s[0:1], v132, s69, v[226:227]
	global_load_dwordx3 v[184:186], v[236:237], off nt
	v_add_u32_e32 v132, 34, v130
	v_mad_u64_u32 v[236:237], s[0:1], v132, s69, v[226:227]
	global_load_dwordx3 v[188:190], v[236:237], off nt
	v_add_u32_e32 v132, 35, v130
	v_mad_u64_u32 v[236:237], s[0:1], v132, s69, v[226:227]
	global_load_dwordx3 v[192:194], v[236:237], off nt
	v_add_u32_e32 v132, 36, v130
	v_mad_u64_u32 v[236:237], s[0:1], v132, s69, v[226:227]
	global_load_dwordx3 v[214:216], v[236:237], off nt
	v_add_u32_e32 v132, 37, v130
	v_mad_u64_u32 v[236:237], s[0:1], v132, s69, v[226:227]
	global_load_dwordx3 v[218:220], v[236:237], off nt
	v_add_u32_e32 v132, 38, v130
	v_mad_u64_u32 v[236:237], s[0:1], v132, s69, v[226:227]
	global_load_dwordx3 v[228:230], v[236:237], off nt
	v_add_u32_e32 v132, 39, v130
	v_mad_u64_u32 v[236:237], s[0:1], v132, s69, v[226:227]
	global_load_dwordx3 v[232:234], v[236:237], off nt
	s_waitcnt vmcnt(19)
	s_nop 1
	v_mfma_f32_16x16x32_bf16 v[10:13], v[122:125], v[110:113], v[10:13]
	v_mfma_f32_16x16x32_bf16 v[6:9], v[122:125], v[114:117], v[6:9]
	v_mfma_f32_16x16x32_bf16 v[2:5], v[122:125], v[118:121], v[2:5]
	s_add_u32 s32, s32, 0x400
	s_addc_u32 s33, s33, 0
	global_load_dwordx4 v[122:125], v134, s[32:33]
	s_waitcnt vmcnt(19)
	v_mfma_f32_16x16x32_bf16 v[70:73], v[126:129], v[110:113], v[70:73]
	v_mfma_f32_16x16x32_bf16 v[46:49], v[126:129], v[114:117], v[46:49]
	v_mfma_f32_16x16x32_bf16 v[18:21], v[126:129], v[118:121], v[18:21]
	s_add_u32 s32, s32, 0x400
	s_addc_u32 s33, s33, 0
	global_load_dwordx4 v[126:129], v134, s[32:33]
	s_waitcnt vmcnt(19)
	v_mfma_f32_16x16x32_bf16 v[66:69], v[138:141], v[110:113], v[66:69]
	v_mfma_f32_16x16x32_bf16 v[42:45], v[138:141], v[114:117], v[42:45]
	v_mfma_f32_16x16x32_bf16 v[14:17], v[138:141], v[118:121], v[14:17]
	s_add_u32 s32, s32, 0x400
	s_addc_u32 s33, s33, 0
	global_load_dwordx4 v[138:141], v134, s[32:33]
	s_waitcnt vmcnt(19)
	v_mfma_f32_16x16x32_bf16 v[78:81], v[142:145], v[110:113], v[78:81]
	v_mfma_f32_16x16x32_bf16 v[50:53], v[142:145], v[114:117], v[50:53]
	v_mfma_f32_16x16x32_bf16 v[22:25], v[142:145], v[118:121], v[22:25]
	s_add_u32 s32, s32, 0x400
	s_addc_u32 s33, s33, 0
	global_load_dwordx4 v[142:145], v134, s[32:33]
	s_waitcnt vmcnt(19)
	v_mfma_f32_16x16x32_bf16 v[82:85], v[146:149], v[110:113], v[82:85]
	v_mfma_f32_16x16x32_bf16 v[58:61], v[146:149], v[114:117], v[58:61]
	v_mfma_f32_16x16x32_bf16 v[30:33], v[146:149], v[118:121], v[30:33]
	s_add_u32 s32, s32, 0x400
	s_addc_u32 s33, s33, 0
	global_load_dwordx4 v[146:149], v134, s[32:33]
	s_waitcnt vmcnt(19)
	v_mfma_f32_16x16x32_bf16 v[86:89], v[150:153], v[110:113], v[86:89]
	v_mfma_f32_16x16x32_bf16 v[54:57], v[150:153], v[114:117], v[54:57]
	v_mfma_f32_16x16x32_bf16 v[26:29], v[150:153], v[118:121], v[26:29]
	s_add_u32 s32, s32, 0x400
	s_addc_u32 s33, s33, 0
	global_load_dwordx4 v[150:153], v134, s[32:33]
	s_waitcnt vmcnt(19)
	v_mfma_f32_16x16x32_bf16 v[94:97], v[154:157], v[110:113], v[94:97]
	v_mfma_f32_16x16x32_bf16 v[62:65], v[154:157], v[114:117], v[62:65]
	v_mfma_f32_16x16x32_bf16 v[34:37], v[154:157], v[118:121], v[34:37]
	s_add_u32 s32, s32, 0x400
	s_addc_u32 s33, s33, 0
	global_load_dwordx4 v[154:157], v134, s[32:33]
	s_waitcnt vmcnt(19)
	v_mfma_f32_16x16x32_bf16 v[98:101], v[158:161], v[110:113], v[98:101]
	v_mfma_f32_16x16x32_bf16 v[74:77], v[158:161], v[114:117], v[74:77]
	v_mfma_f32_16x16x32_bf16 v[38:41], v[158:161], v[118:121], v[38:41]
	s_add_u32 s32, s32, 0x400
	s_addc_u32 s33, s33, 0
	global_load_dwordx4 v[158:161], v134, s[32:33]
	s_waitcnt vmcnt(19)
	v_mfma_f32_16x16x32_bf16 v[106:109], v[162:165], v[110:113], v[106:109]
	v_mfma_f32_16x16x32_bf16 v[102:105], v[162:165], v[114:117], v[102:105]
	v_mfma_f32_16x16x32_bf16 v[90:93], v[162:165], v[118:121], v[90:93]
	s_add_u32 s32, s32, 0x400
	s_addc_u32 s33, s33, 0
	global_load_dwordx4 v[162:165], v134, s[32:33]
	s_waitcnt vmcnt(9)
	v_cvt_pk_bf16_f32 v110, v166, v184
	v_cvt_pk_bf16_f32 v111, v188, v192
	v_cvt_pk_bf16_f32 v112, v214, v218
	v_cvt_pk_bf16_f32 v113, v228, v232
	v_cvt_pk_bf16_f32 v114, v167, v185
	v_cvt_pk_bf16_f32 v115, v189, v193
	v_cvt_pk_bf16_f32 v116, v215, v219
	v_cvt_pk_bf16_f32 v117, v229, v233
	v_cvt_pk_bf16_f32 v118, v168, v186
	v_cvt_pk_bf16_f32 v119, v190, v194
	v_cvt_pk_bf16_f32 v120, v216, v220
	v_cvt_pk_bf16_f32 v121, v230, v234
	v_add_u32_e32 v132, 64, v130
	v_mad_u64_u32 v[236:237], s[0:1], v132, s69, v[226:227]
	global_load_dwordx3 v[166:168], v[236:237], off nt
	v_add_u32_e32 v132, 65, v130
	v_mad_u64_u32 v[236:237], s[0:1], v132, s69, v[226:227]
	global_load_dwordx3 v[184:186], v[236:237], off nt
	v_add_u32_e32 v132, 66, v130
	v_mad_u64_u32 v[236:237], s[0:1], v132, s69, v[226:227]
	global_load_dwordx3 v[188:190], v[236:237], off nt
	v_add_u32_e32 v132, 67, v130
	v_mad_u64_u32 v[236:237], s[0:1], v132, s69, v[226:227]
	global_load_dwordx3 v[192:194], v[236:237], off nt
	v_add_u32_e32 v132, 68, v130
	v_mad_u64_u32 v[236:237], s[0:1], v132, s69, v[226:227]
	global_load_dwordx3 v[214:216], v[236:237], off nt
	v_add_u32_e32 v132, 69, v130
	v_mad_u64_u32 v[236:237], s[0:1], v132, s69, v[226:227]
	global_load_dwordx3 v[218:220], v[236:237], off nt
	v_add_u32_e32 v132, 70, v130
	v_mad_u64_u32 v[236:237], s[0:1], v132, s69, v[226:227]
	global_load_dwordx3 v[228:230], v[236:237], off nt
	v_add_u32_e32 v132, 71, v130
	v_mad_u64_u32 v[236:237], s[0:1], v132, s69, v[226:227]
	global_load_dwordx3 v[232:234], v[236:237], off nt
	s_nop 1
	v_mfma_f32_16x16x32_bf16 v[10:13], v[172:175], v[110:113], v[10:13]
	v_mfma_f32_16x16x32_bf16 v[6:9], v[172:175], v[114:117], v[6:9]
	v_mfma_f32_16x16x32_bf16 v[2:5], v[172:175], v[118:121], v[2:5]
	s_add_u32 s32, s32, 0x400
	s_addc_u32 s33, s33, 0
	global_load_dwordx4 v[172:175], v134, s[32:33]
	v_mfma_f32_16x16x32_bf16 v[70:73], v[176:179], v[110:113], v[70:73]
	v_mfma_f32_16x16x32_bf16 v[46:49], v[176:179], v[114:117], v[46:49]
	v_mfma_f32_16x16x32_bf16 v[18:21], v[176:179], v[118:121], v[18:21]
	s_add_u32 s32, s32, 0x400
	s_addc_u32 s33, s33, 0
	global_load_dwordx4 v[176:179], v134, s[32:33]
	v_mfma_f32_16x16x32_bf16 v[66:69], v[180:183], v[110:113], v[66:69]
	v_mfma_f32_16x16x32_bf16 v[42:45], v[180:183], v[114:117], v[42:45]
	v_mfma_f32_16x16x32_bf16 v[14:17], v[180:183], v[118:121], v[14:17]
	s_add_u32 s32, s32, 0x400
	s_addc_u32 s33, s33, 0
	global_load_dwordx4 v[180:183], v134, s[32:33]
	s_waitcnt vmcnt(19)
	v_mfma_f32_16x16x32_bf16 v[78:81], v[122:125], v[110:113], v[78:81]
	v_mfma_f32_16x16x32_bf16 v[50:53], v[122:125], v[114:117], v[50:53]
	v_mfma_f32_16x16x32_bf16 v[22:25], v[122:125], v[118:121], v[22:25]
	s_add_u32 s32, s32, 0x400
	s_addc_u32 s33, s33, 0
	global_load_dwordx4 v[122:125], v134, s[32:33]
	s_waitcnt vmcnt(19)
	v_mfma_f32_16x16x32_bf16 v[82:85], v[126:129], v[110:113], v[82:85]
	v_mfma_f32_16x16x32_bf16 v[58:61], v[126:129], v[114:117], v[58:61]
	v_mfma_f32_16x16x32_bf16 v[30:33], v[126:129], v[118:121], v[30:33]
	s_add_u32 s32, s32, 0x400
	s_addc_u32 s33, s33, 0
	global_load_dwordx4 v[126:129], v134, s[32:33]
	s_waitcnt vmcnt(19)
	v_mfma_f32_16x16x32_bf16 v[86:89], v[138:141], v[110:113], v[86:89]
	v_mfma_f32_16x16x32_bf16 v[54:57], v[138:141], v[114:117], v[54:57]
	v_mfma_f32_16x16x32_bf16 v[26:29], v[138:141], v[118:121], v[26:29]
	s_add_u32 s32, s32, 0x400
	s_addc_u32 s33, s33, 0
	global_load_dwordx4 v[138:141], v134, s[32:33]
	s_waitcnt vmcnt(19)
	v_mfma_f32_16x16x32_bf16 v[94:97], v[142:145], v[110:113], v[94:97]
	v_mfma_f32_16x16x32_bf16 v[62:65], v[142:145], v[114:117], v[62:65]
	v_mfma_f32_16x16x32_bf16 v[34:37], v[142:145], v[118:121], v[34:37]
	s_add_u32 s32, s32, 0x400
	s_addc_u32 s33, s33, 0
	global_load_dwordx4 v[142:145], v134, s[32:33]
	s_waitcnt vmcnt(19)
	v_mfma_f32_16x16x32_bf16 v[98:101], v[146:149], v[110:113], v[98:101]
	v_mfma_f32_16x16x32_bf16 v[74:77], v[146:149], v[114:117], v[74:77]
	v_mfma_f32_16x16x32_bf16 v[38:41], v[146:149], v[118:121], v[38:41]
	s_add_u32 s32, s32, 0x400
	s_addc_u32 s33, s33, 0
	global_load_dwordx4 v[146:149], v134, s[32:33]
	s_waitcnt vmcnt(19)
	v_mfma_f32_16x16x32_bf16 v[106:109], v[150:153], v[110:113], v[106:109]
	v_mfma_f32_16x16x32_bf16 v[102:105], v[150:153], v[114:117], v[102:105]
	v_mfma_f32_16x16x32_bf16 v[90:93], v[150:153], v[118:121], v[90:93]
	s_add_u32 s32, s32, 0x400
	s_addc_u32 s33, s33, 0
	global_load_dwordx4 v[150:153], v134, s[32:33]
	s_waitcnt vmcnt(9)
	v_cvt_pk_bf16_f32 v110, v166, v184
	v_cvt_pk_bf16_f32 v111, v188, v192
	v_cvt_pk_bf16_f32 v112, v214, v218
	v_cvt_pk_bf16_f32 v113, v228, v232
	v_cvt_pk_bf16_f32 v114, v167, v185
	v_cvt_pk_bf16_f32 v115, v189, v193
	v_cvt_pk_bf16_f32 v116, v215, v219
	v_cvt_pk_bf16_f32 v117, v229, v233
	v_cvt_pk_bf16_f32 v118, v168, v186
	v_cvt_pk_bf16_f32 v119, v190, v194
	v_cvt_pk_bf16_f32 v120, v216, v220
	v_cvt_pk_bf16_f32 v121, v230, v234
	v_add_u32_e32 v132, 96, v130
	v_mad_u64_u32 v[236:237], s[0:1], v132, s69, v[226:227]
	global_load_dwordx3 v[166:168], v[236:237], off nt
	v_add_u32_e32 v132, 97, v130
	v_mad_u64_u32 v[236:237], s[0:1], v132, s69, v[226:227]
	global_load_dwordx3 v[184:186], v[236:237], off nt
	v_add_u32_e32 v132, 98, v130
	v_mad_u64_u32 v[236:237], s[0:1], v132, s69, v[226:227]
	global_load_dwordx3 v[188:190], v[236:237], off nt
	v_add_u32_e32 v132, 99, v130
	v_mad_u64_u32 v[236:237], s[0:1], v132, s69, v[226:227]
	global_load_dwordx3 v[192:194], v[236:237], off nt
	v_add_u32_e32 v132, 100, v130
	v_mad_u64_u32 v[236:237], s[0:1], v132, s69, v[226:227]
	global_load_dwordx3 v[214:216], v[236:237], off nt
	v_add_u32_e32 v132, 101, v130
	v_mad_u64_u32 v[236:237], s[0:1], v132, s69, v[226:227]
	global_load_dwordx3 v[218:220], v[236:237], off nt
	v_add_u32_e32 v132, 102, v130
	v_mad_u64_u32 v[236:237], s[0:1], v132, s69, v[226:227]
	global_load_dwordx3 v[228:230], v[236:237], off nt
	v_add_u32_e32 v132, 103, v130
	v_mad_u64_u32 v[236:237], s[0:1], v132, s69, v[226:227]
	global_load_dwordx3 v[232:234], v[236:237], off nt
	s_nop 1
	v_mfma_f32_16x16x32_bf16 v[10:13], v[154:157], v[110:113], v[10:13]
	v_mfma_f32_16x16x32_bf16 v[6:9], v[154:157], v[114:117], v[6:9]
	v_mfma_f32_16x16x32_bf16 v[2:5], v[154:157], v[118:121], v[2:5]
	s_add_u32 s32, s32, 0x400
	s_addc_u32 s33, s33, 0
	global_load_dwordx4 v[154:157], v134, s[32:33]
	v_mfma_f32_16x16x32_bf16 v[70:73], v[158:161], v[110:113], v[70:73]
	v_mfma_f32_16x16x32_bf16 v[46:49], v[158:161], v[114:117], v[46:49]
	v_mfma_f32_16x16x32_bf16 v[18:21], v[158:161], v[118:121], v[18:21]
	s_add_u32 s32, s32, 0x400
	s_addc_u32 s33, s33, 0
	global_load_dwordx4 v[158:161], v134, s[32:33]
	v_mfma_f32_16x16x32_bf16 v[66:69], v[162:165], v[110:113], v[66:69]
	v_mfma_f32_16x16x32_bf16 v[42:45], v[162:165], v[114:117], v[42:45]
	v_mfma_f32_16x16x32_bf16 v[14:17], v[162:165], v[118:121], v[14:17]
	s_add_u32 s32, s32, 0x400
	s_addc_u32 s33, s33, 0
	global_load_dwordx4 v[162:165], v134, s[32:33]
	s_waitcnt vmcnt(19)
	v_mfma_f32_16x16x32_bf16 v[78:81], v[172:175], v[110:113], v[78:81]
	v_mfma_f32_16x16x32_bf16 v[50:53], v[172:175], v[114:117], v[50:53]
	v_mfma_f32_16x16x32_bf16 v[22:25], v[172:175], v[118:121], v[22:25]
	s_add_u32 s32, s32, 0x400
	s_addc_u32 s33, s33, 0
	global_load_dwordx4 v[172:175], v134, s[32:33]
	s_waitcnt vmcnt(19)
	v_mfma_f32_16x16x32_bf16 v[82:85], v[176:179], v[110:113], v[82:85]
	v_mfma_f32_16x16x32_bf16 v[58:61], v[176:179], v[114:117], v[58:61]
	v_mfma_f32_16x16x32_bf16 v[30:33], v[176:179], v[118:121], v[30:33]
	s_add_u32 s32, s32, 0x400
	s_addc_u32 s33, s33, 0
	global_load_dwordx4 v[176:179], v134, s[32:33]
	s_waitcnt vmcnt(19)
	v_mfma_f32_16x16x32_bf16 v[86:89], v[180:183], v[110:113], v[86:89]
	v_mfma_f32_16x16x32_bf16 v[54:57], v[180:183], v[114:117], v[54:57]
	v_mfma_f32_16x16x32_bf16 v[26:29], v[180:183], v[118:121], v[26:29]
	s_add_u32 s32, s32, 0x400
	s_addc_u32 s33, s33, 0
	global_load_dwordx4 v[180:183], v134, s[32:33]
	s_waitcnt vmcnt(19)
	v_mfma_f32_16x16x32_bf16 v[94:97], v[122:125], v[110:113], v[94:97]
	v_mfma_f32_16x16x32_bf16 v[62:65], v[122:125], v[114:117], v[62:65]
	v_mfma_f32_16x16x32_bf16 v[34:37], v[122:125], v[118:121], v[34:37]
	s_add_u32 s32, s32, 0x400
	s_addc_u32 s33, s33, 0
	global_load_dwordx4 v[122:125], v134, s[32:33]
	s_waitcnt vmcnt(19)
	v_mfma_f32_16x16x32_bf16 v[98:101], v[126:129], v[110:113], v[98:101]
	v_mfma_f32_16x16x32_bf16 v[74:77], v[126:129], v[114:117], v[74:77]
	v_mfma_f32_16x16x32_bf16 v[38:41], v[126:129], v[118:121], v[38:41]
	s_add_u32 s32, s32, 0x400
	s_addc_u32 s33, s33, 0
	global_load_dwordx4 v[126:129], v134, s[32:33]
	s_waitcnt vmcnt(19)
	v_mfma_f32_16x16x32_bf16 v[106:109], v[138:141], v[110:113], v[106:109]
	v_mfma_f32_16x16x32_bf16 v[102:105], v[138:141], v[114:117], v[102:105]
	v_mfma_f32_16x16x32_bf16 v[90:93], v[138:141], v[118:121], v[90:93]
	s_add_u32 s32, s32, 0x400
	s_addc_u32 s33, s33, 0
	global_load_dwordx4 v[138:141], v134, s[32:33]
	s_waitcnt vmcnt(9)
	v_cvt_pk_bf16_f32 v110, v166, v184
	v_cvt_pk_bf16_f32 v111, v188, v192
	v_cvt_pk_bf16_f32 v112, v214, v218
	v_cvt_pk_bf16_f32 v113, v228, v232
	v_cvt_pk_bf16_f32 v114, v167, v185
	v_cvt_pk_bf16_f32 v115, v189, v193
	v_cvt_pk_bf16_f32 v116, v215, v219
	v_cvt_pk_bf16_f32 v117, v229, v233
	v_cvt_pk_bf16_f32 v118, v168, v186
	v_cvt_pk_bf16_f32 v119, v190, v194
	v_cvt_pk_bf16_f32 v120, v216, v220
	v_cvt_pk_bf16_f32 v121, v230, v234
	v_add_u32_e32 v132, 128, v130
	v_mad_u64_u32 v[236:237], s[0:1], v132, s69, v[226:227]
	global_load_dwordx3 v[166:168], v[236:237], off nt
	v_add_u32_e32 v132, 129, v130
	v_mad_u64_u32 v[236:237], s[0:1], v132, s69, v[226:227]
	global_load_dwordx3 v[184:186], v[236:237], off nt
	v_add_u32_e32 v132, 130, v130
	v_mad_u64_u32 v[236:237], s[0:1], v132, s69, v[226:227]
	global_load_dwordx3 v[188:190], v[236:237], off nt
	v_add_u32_e32 v132, 131, v130
	v_mad_u64_u32 v[236:237], s[0:1], v132, s69, v[226:227]
	global_load_dwordx3 v[192:194], v[236:237], off nt
	v_add_u32_e32 v132, 132, v130
	v_mad_u64_u32 v[236:237], s[0:1], v132, s69, v[226:227]
	global_load_dwordx3 v[214:216], v[236:237], off nt
	v_add_u32_e32 v132, 133, v130
	v_mad_u64_u32 v[236:237], s[0:1], v132, s69, v[226:227]
	global_load_dwordx3 v[218:220], v[236:237], off nt
	v_add_u32_e32 v132, 134, v130
	v_mad_u64_u32 v[236:237], s[0:1], v132, s69, v[226:227]
	global_load_dwordx3 v[228:230], v[236:237], off nt
	v_add_u32_e32 v132, 135, v130
	v_mad_u64_u32 v[236:237], s[0:1], v132, s69, v[226:227]
	global_load_dwordx3 v[232:234], v[236:237], off nt
	s_nop 1
	v_mfma_f32_16x16x32_bf16 v[10:13], v[142:145], v[110:113], v[10:13]
	v_mfma_f32_16x16x32_bf16 v[6:9], v[142:145], v[114:117], v[6:9]
	v_mfma_f32_16x16x32_bf16 v[2:5], v[142:145], v[118:121], v[2:5]
	s_add_u32 s32, s32, 0x400
	s_addc_u32 s33, s33, 0
	global_load_dwordx4 v[142:145], v134, s[32:33]
	v_mfma_f32_16x16x32_bf16 v[70:73], v[146:149], v[110:113], v[70:73]
	v_mfma_f32_16x16x32_bf16 v[46:49], v[146:149], v[114:117], v[46:49]
	v_mfma_f32_16x16x32_bf16 v[18:21], v[146:149], v[118:121], v[18:21]
	s_add_u32 s32, s32, 0x400
	s_addc_u32 s33, s33, 0
	global_load_dwordx4 v[146:149], v134, s[32:33]
	v_mfma_f32_16x16x32_bf16 v[66:69], v[150:153], v[110:113], v[66:69]
	v_mfma_f32_16x16x32_bf16 v[42:45], v[150:153], v[114:117], v[42:45]
	v_mfma_f32_16x16x32_bf16 v[14:17], v[150:153], v[118:121], v[14:17]
	s_add_u32 s32, s32, 0x400
	s_addc_u32 s33, s33, 0
	global_load_dwordx4 v[150:153], v134, s[32:33]
	s_waitcnt vmcnt(19)
	v_mfma_f32_16x16x32_bf16 v[78:81], v[154:157], v[110:113], v[78:81]
	v_mfma_f32_16x16x32_bf16 v[50:53], v[154:157], v[114:117], v[50:53]
	v_mfma_f32_16x16x32_bf16 v[22:25], v[154:157], v[118:121], v[22:25]
	s_add_u32 s32, s32, 0x400
	s_addc_u32 s33, s33, 0
	global_load_dwordx4 v[154:157], v134, s[32:33]
	s_waitcnt vmcnt(19)
	v_mfma_f32_16x16x32_bf16 v[82:85], v[158:161], v[110:113], v[82:85]
	v_mfma_f32_16x16x32_bf16 v[58:61], v[158:161], v[114:117], v[58:61]
	v_mfma_f32_16x16x32_bf16 v[30:33], v[158:161], v[118:121], v[30:33]
	s_add_u32 s32, s32, 0x400
	s_addc_u32 s33, s33, 0
	global_load_dwordx4 v[158:161], v134, s[32:33]
	s_waitcnt vmcnt(19)
	v_mfma_f32_16x16x32_bf16 v[86:89], v[162:165], v[110:113], v[86:89]
	v_mfma_f32_16x16x32_bf16 v[54:57], v[162:165], v[114:117], v[54:57]
	v_mfma_f32_16x16x32_bf16 v[26:29], v[162:165], v[118:121], v[26:29]
	s_add_u32 s32, s32, 0x400
	s_addc_u32 s33, s33, 0
	global_load_dwordx4 v[162:165], v134, s[32:33]
	s_waitcnt vmcnt(19)
	v_mfma_f32_16x16x32_bf16 v[94:97], v[172:175], v[110:113], v[94:97]
	v_mfma_f32_16x16x32_bf16 v[62:65], v[172:175], v[114:117], v[62:65]
	v_mfma_f32_16x16x32_bf16 v[34:37], v[172:175], v[118:121], v[34:37]
	s_add_u32 s32, s32, 0x400
	s_addc_u32 s33, s33, 0
	global_load_dwordx4 v[172:175], v134, s[32:33]
	s_waitcnt vmcnt(19)
	v_mfma_f32_16x16x32_bf16 v[98:101], v[176:179], v[110:113], v[98:101]
	v_mfma_f32_16x16x32_bf16 v[74:77], v[176:179], v[114:117], v[74:77]
	v_mfma_f32_16x16x32_bf16 v[38:41], v[176:179], v[118:121], v[38:41]
	s_add_u32 s32, s32, 0x400
	s_addc_u32 s33, s33, 0
	global_load_dwordx4 v[176:179], v134, s[32:33]
	s_waitcnt vmcnt(19)
	v_mfma_f32_16x16x32_bf16 v[106:109], v[180:183], v[110:113], v[106:109]
	v_mfma_f32_16x16x32_bf16 v[102:105], v[180:183], v[114:117], v[102:105]
	v_mfma_f32_16x16x32_bf16 v[90:93], v[180:183], v[118:121], v[90:93]
	s_add_u32 s32, s32, 0x400
	s_addc_u32 s33, s33, 0
	global_load_dwordx4 v[180:183], v134, s[32:33]
	s_waitcnt vmcnt(9)
	v_cvt_pk_bf16_f32 v110, v166, v184
	v_cvt_pk_bf16_f32 v111, v188, v192
	v_cvt_pk_bf16_f32 v112, v214, v218
	v_cvt_pk_bf16_f32 v113, v228, v232
	v_cvt_pk_bf16_f32 v114, v167, v185
	v_cvt_pk_bf16_f32 v115, v189, v193
	v_cvt_pk_bf16_f32 v116, v215, v219
	v_cvt_pk_bf16_f32 v117, v229, v233
	v_cvt_pk_bf16_f32 v118, v168, v186
	v_cvt_pk_bf16_f32 v119, v190, v194
	v_cvt_pk_bf16_f32 v120, v216, v220
	v_cvt_pk_bf16_f32 v121, v230, v234
	v_add_u32_e32 v132, 160, v130
	v_mad_u64_u32 v[236:237], s[0:1], v132, s69, v[226:227]
	global_load_dwordx3 v[166:168], v[236:237], off nt
	v_add_u32_e32 v132, 161, v130
	v_mad_u64_u32 v[236:237], s[0:1], v132, s69, v[226:227]
	global_load_dwordx3 v[184:186], v[236:237], off nt
	v_add_u32_e32 v132, 162, v130
	v_mad_u64_u32 v[236:237], s[0:1], v132, s69, v[226:227]
	global_load_dwordx3 v[188:190], v[236:237], off nt
	v_add_u32_e32 v132, 163, v130
	v_mad_u64_u32 v[236:237], s[0:1], v132, s69, v[226:227]
	global_load_dwordx3 v[192:194], v[236:237], off nt
	v_add_u32_e32 v132, 164, v130
	v_mad_u64_u32 v[236:237], s[0:1], v132, s69, v[226:227]
	global_load_dwordx3 v[214:216], v[236:237], off nt
	v_add_u32_e32 v132, 165, v130
	v_mad_u64_u32 v[236:237], s[0:1], v132, s69, v[226:227]
	global_load_dwordx3 v[218:220], v[236:237], off nt
	v_add_u32_e32 v132, 166, v130
	v_mad_u64_u32 v[236:237], s[0:1], v132, s69, v[226:227]
	global_load_dwordx3 v[228:230], v[236:237], off nt
	v_add_u32_e32 v132, 167, v130
	v_mad_u64_u32 v[236:237], s[0:1], v132, s69, v[226:227]
	global_load_dwordx3 v[232:234], v[236:237], off nt
	s_nop 1
	v_mfma_f32_16x16x32_bf16 v[10:13], v[122:125], v[110:113], v[10:13]
	v_mfma_f32_16x16x32_bf16 v[6:9], v[122:125], v[114:117], v[6:9]
	v_mfma_f32_16x16x32_bf16 v[2:5], v[122:125], v[118:121], v[2:5]
	s_add_u32 s32, s32, 0x400
	s_addc_u32 s33, s33, 0
	global_load_dwordx4 v[122:125], v134, s[32:33]
	v_mfma_f32_16x16x32_bf16 v[70:73], v[126:129], v[110:113], v[70:73]
	v_mfma_f32_16x16x32_bf16 v[46:49], v[126:129], v[114:117], v[46:49]
	v_mfma_f32_16x16x32_bf16 v[18:21], v[126:129], v[118:121], v[18:21]
	s_add_u32 s32, s32, 0x400
	s_addc_u32 s33, s33, 0
	global_load_dwordx4 v[126:129], v134, s[32:33]
	v_mfma_f32_16x16x32_bf16 v[66:69], v[138:141], v[110:113], v[66:69]
	v_mfma_f32_16x16x32_bf16 v[42:45], v[138:141], v[114:117], v[42:45]
	v_mfma_f32_16x16x32_bf16 v[14:17], v[138:141], v[118:121], v[14:17]
	s_add_u32 s32, s32, 0x400
	s_addc_u32 s33, s33, 0
	global_load_dwordx4 v[138:141], v134, s[32:33]
	s_waitcnt vmcnt(19)
	v_mfma_f32_16x16x32_bf16 v[78:81], v[142:145], v[110:113], v[78:81]
	v_mfma_f32_16x16x32_bf16 v[50:53], v[142:145], v[114:117], v[50:53]
	v_mfma_f32_16x16x32_bf16 v[22:25], v[142:145], v[118:121], v[22:25]
	s_add_u32 s32, s32, 0x400
	s_addc_u32 s33, s33, 0
	global_load_dwordx4 v[142:145], v134, s[32:33]
	s_waitcnt vmcnt(19)
	v_mfma_f32_16x16x32_bf16 v[82:85], v[146:149], v[110:113], v[82:85]
	v_mfma_f32_16x16x32_bf16 v[58:61], v[146:149], v[114:117], v[58:61]
	v_mfma_f32_16x16x32_bf16 v[30:33], v[146:149], v[118:121], v[30:33]
	s_add_u32 s32, s32, 0x400
	s_addc_u32 s33, s33, 0
	global_load_dwordx4 v[146:149], v134, s[32:33]
	s_waitcnt vmcnt(19)
	v_mfma_f32_16x16x32_bf16 v[86:89], v[150:153], v[110:113], v[86:89]
	v_mfma_f32_16x16x32_bf16 v[54:57], v[150:153], v[114:117], v[54:57]
	v_mfma_f32_16x16x32_bf16 v[26:29], v[150:153], v[118:121], v[26:29]
	s_add_u32 s32, s32, 0x400
	s_addc_u32 s33, s33, 0
	global_load_dwordx4 v[150:153], v134, s[32:33]
	s_waitcnt vmcnt(19)
	v_mfma_f32_16x16x32_bf16 v[94:97], v[154:157], v[110:113], v[94:97]
	v_mfma_f32_16x16x32_bf16 v[62:65], v[154:157], v[114:117], v[62:65]
	v_mfma_f32_16x16x32_bf16 v[34:37], v[154:157], v[118:121], v[34:37]
	s_add_u32 s32, s32, 0x400
	s_addc_u32 s33, s33, 0
	global_load_dwordx4 v[154:157], v134, s[32:33]
	s_waitcnt vmcnt(19)
	v_mfma_f32_16x16x32_bf16 v[98:101], v[158:161], v[110:113], v[98:101]
	v_mfma_f32_16x16x32_bf16 v[74:77], v[158:161], v[114:117], v[74:77]
	v_mfma_f32_16x16x32_bf16 v[38:41], v[158:161], v[118:121], v[38:41]
	s_add_u32 s32, s32, 0x400
	s_addc_u32 s33, s33, 0
	global_load_dwordx4 v[158:161], v134, s[32:33]
	s_waitcnt vmcnt(19)
	v_mfma_f32_16x16x32_bf16 v[106:109], v[162:165], v[110:113], v[106:109]
	v_mfma_f32_16x16x32_bf16 v[102:105], v[162:165], v[114:117], v[102:105]
	v_mfma_f32_16x16x32_bf16 v[90:93], v[162:165], v[118:121], v[90:93]
	s_add_u32 s32, s32, 0x400
	s_addc_u32 s33, s33, 0
	global_load_dwordx4 v[162:165], v134, s[32:33]
	s_waitcnt vmcnt(9)
	v_cvt_pk_bf16_f32 v110, v166, v184
	v_cvt_pk_bf16_f32 v111, v188, v192
	v_cvt_pk_bf16_f32 v112, v214, v218
	v_cvt_pk_bf16_f32 v113, v228, v232
	v_cvt_pk_bf16_f32 v114, v167, v185
	v_cvt_pk_bf16_f32 v115, v189, v193
	v_cvt_pk_bf16_f32 v116, v215, v219
	v_cvt_pk_bf16_f32 v117, v229, v233
	v_cvt_pk_bf16_f32 v118, v168, v186
	v_cvt_pk_bf16_f32 v119, v190, v194
	v_cvt_pk_bf16_f32 v120, v216, v220
	v_cvt_pk_bf16_f32 v121, v230, v234
	v_add_u32_e32 v132, 192, v130
	v_mad_u64_u32 v[236:237], s[0:1], v132, s69, v[226:227]
	global_load_dwordx3 v[166:168], v[236:237], off nt
	v_add_u32_e32 v132, 193, v130
	v_mad_u64_u32 v[236:237], s[0:1], v132, s69, v[226:227]
	global_load_dwordx3 v[184:186], v[236:237], off nt
	v_add_u32_e32 v132, 194, v130
	v_mad_u64_u32 v[236:237], s[0:1], v132, s69, v[226:227]
	global_load_dwordx3 v[188:190], v[236:237], off nt
	v_add_u32_e32 v132, 195, v130
	v_mad_u64_u32 v[236:237], s[0:1], v132, s69, v[226:227]
	global_load_dwordx3 v[192:194], v[236:237], off nt
	v_add_u32_e32 v132, 196, v130
	v_mad_u64_u32 v[236:237], s[0:1], v132, s69, v[226:227]
	global_load_dwordx3 v[214:216], v[236:237], off nt
	v_add_u32_e32 v132, 197, v130
	v_mad_u64_u32 v[236:237], s[0:1], v132, s69, v[226:227]
	global_load_dwordx3 v[218:220], v[236:237], off nt
	v_add_u32_e32 v132, 198, v130
	v_mad_u64_u32 v[236:237], s[0:1], v132, s69, v[226:227]
	global_load_dwordx3 v[228:230], v[236:237], off nt
	v_add_u32_e32 v132, 199, v130
	v_mad_u64_u32 v[236:237], s[0:1], v132, s69, v[226:227]
	global_load_dwordx3 v[232:234], v[236:237], off nt
	s_nop 1
	v_mfma_f32_16x16x32_bf16 v[10:13], v[172:175], v[110:113], v[10:13]
	v_mfma_f32_16x16x32_bf16 v[6:9], v[172:175], v[114:117], v[6:9]
	v_mfma_f32_16x16x32_bf16 v[2:5], v[172:175], v[118:121], v[2:5]
	s_add_u32 s32, s32, 0x400
	s_addc_u32 s33, s33, 0
	global_load_dwordx4 v[172:175], v134, s[32:33]
	v_mfma_f32_16x16x32_bf16 v[70:73], v[176:179], v[110:113], v[70:73]
	v_mfma_f32_16x16x32_bf16 v[46:49], v[176:179], v[114:117], v[46:49]
	v_mfma_f32_16x16x32_bf16 v[18:21], v[176:179], v[118:121], v[18:21]
	s_add_u32 s32, s32, 0x400
	s_addc_u32 s33, s33, 0
	global_load_dwordx4 v[176:179], v134, s[32:33]
	v_mfma_f32_16x16x32_bf16 v[66:69], v[180:183], v[110:113], v[66:69]
	v_mfma_f32_16x16x32_bf16 v[42:45], v[180:183], v[114:117], v[42:45]
	v_mfma_f32_16x16x32_bf16 v[14:17], v[180:183], v[118:121], v[14:17]
	s_add_u32 s32, s32, 0x400
	s_addc_u32 s33, s33, 0
	global_load_dwordx4 v[180:183], v134, s[32:33]
	s_waitcnt vmcnt(19)
	v_mfma_f32_16x16x32_bf16 v[78:81], v[122:125], v[110:113], v[78:81]
	v_mfma_f32_16x16x32_bf16 v[50:53], v[122:125], v[114:117], v[50:53]
	v_mfma_f32_16x16x32_bf16 v[22:25], v[122:125], v[118:121], v[22:25]
	s_add_u32 s32, s32, 0x400
	s_addc_u32 s33, s33, 0
	global_load_dwordx4 v[122:125], v134, s[32:33]
	s_waitcnt vmcnt(19)
	v_mfma_f32_16x16x32_bf16 v[82:85], v[126:129], v[110:113], v[82:85]
	v_mfma_f32_16x16x32_bf16 v[58:61], v[126:129], v[114:117], v[58:61]
	v_mfma_f32_16x16x32_bf16 v[30:33], v[126:129], v[118:121], v[30:33]
	s_add_u32 s32, s32, 0x400
	s_addc_u32 s33, s33, 0
	global_load_dwordx4 v[126:129], v134, s[32:33]
	s_waitcnt vmcnt(19)
	v_mfma_f32_16x16x32_bf16 v[86:89], v[138:141], v[110:113], v[86:89]
	v_mfma_f32_16x16x32_bf16 v[54:57], v[138:141], v[114:117], v[54:57]
	v_mfma_f32_16x16x32_bf16 v[26:29], v[138:141], v[118:121], v[26:29]
	s_add_u32 s32, s32, 0x400
	s_addc_u32 s33, s33, 0
	global_load_dwordx4 v[138:141], v134, s[32:33]
	s_waitcnt vmcnt(19)
	v_mfma_f32_16x16x32_bf16 v[94:97], v[142:145], v[110:113], v[94:97]
	v_mfma_f32_16x16x32_bf16 v[62:65], v[142:145], v[114:117], v[62:65]
	v_mfma_f32_16x16x32_bf16 v[34:37], v[142:145], v[118:121], v[34:37]
	s_add_u32 s32, s32, 0x400
	s_addc_u32 s33, s33, 0
	global_load_dwordx4 v[142:145], v134, s[32:33]
	s_waitcnt vmcnt(19)
	v_mfma_f32_16x16x32_bf16 v[98:101], v[146:149], v[110:113], v[98:101]
	v_mfma_f32_16x16x32_bf16 v[74:77], v[146:149], v[114:117], v[74:77]
	v_mfma_f32_16x16x32_bf16 v[38:41], v[146:149], v[118:121], v[38:41]
	s_add_u32 s32, s32, 0x400
	s_addc_u32 s33, s33, 0
	global_load_dwordx4 v[146:149], v134, s[32:33]
	s_waitcnt vmcnt(19)
	v_mfma_f32_16x16x32_bf16 v[106:109], v[150:153], v[110:113], v[106:109]
	v_mfma_f32_16x16x32_bf16 v[102:105], v[150:153], v[114:117], v[102:105]
	v_mfma_f32_16x16x32_bf16 v[90:93], v[150:153], v[118:121], v[90:93]
	s_add_u32 s32, s32, 0x400
	s_addc_u32 s33, s33, 0
	global_load_dwordx4 v[150:153], v134, s[32:33]
	s_waitcnt vmcnt(9)
	v_cvt_pk_bf16_f32 v110, v166, v184
	v_cvt_pk_bf16_f32 v111, v188, v192
	v_cvt_pk_bf16_f32 v112, v214, v218
	v_cvt_pk_bf16_f32 v113, v228, v232
	v_cvt_pk_bf16_f32 v114, v167, v185
	v_cvt_pk_bf16_f32 v115, v189, v193
	v_cvt_pk_bf16_f32 v116, v215, v219
	v_cvt_pk_bf16_f32 v117, v229, v233
	v_cvt_pk_bf16_f32 v118, v168, v186
	v_cvt_pk_bf16_f32 v119, v190, v194
	v_cvt_pk_bf16_f32 v120, v216, v220
	v_cvt_pk_bf16_f32 v121, v230, v234
	v_add_u32_e32 v132, 224, v130
	v_mad_u64_u32 v[236:237], s[0:1], v132, s69, v[226:227]
	global_load_dwordx3 v[166:168], v[236:237], off nt
	v_add_u32_e32 v132, 225, v130
	v_mad_u64_u32 v[236:237], s[0:1], v132, s69, v[226:227]
	global_load_dwordx3 v[184:186], v[236:237], off nt
	v_add_u32_e32 v132, 226, v130
	v_mad_u64_u32 v[236:237], s[0:1], v132, s69, v[226:227]
	global_load_dwordx3 v[188:190], v[236:237], off nt
	v_add_u32_e32 v132, 227, v130
	v_mad_u64_u32 v[236:237], s[0:1], v132, s69, v[226:227]
	global_load_dwordx3 v[192:194], v[236:237], off nt
	v_add_u32_e32 v132, 228, v130
	v_mad_u64_u32 v[236:237], s[0:1], v132, s69, v[226:227]
	global_load_dwordx3 v[214:216], v[236:237], off nt
	v_add_u32_e32 v132, 229, v130
	v_mad_u64_u32 v[236:237], s[0:1], v132, s69, v[226:227]
	global_load_dwordx3 v[218:220], v[236:237], off nt
	v_add_u32_e32 v132, 230, v130
	v_mad_u64_u32 v[236:237], s[0:1], v132, s69, v[226:227]
	global_load_dwordx3 v[228:230], v[236:237], off nt
	v_add_u32_e32 v132, 231, v130
	v_mad_u64_u32 v[236:237], s[0:1], v132, s69, v[226:227]
	global_load_dwordx3 v[232:234], v[236:237], off nt
	s_nop 1
	v_mfma_f32_16x16x32_bf16 v[10:13], v[154:157], v[110:113], v[10:13]
	v_mfma_f32_16x16x32_bf16 v[6:9], v[154:157], v[114:117], v[6:9]
	v_mfma_f32_16x16x32_bf16 v[2:5], v[154:157], v[118:121], v[2:5]
	s_add_u32 s32, s32, 0x400
	s_addc_u32 s33, s33, 0
	global_load_dwordx4 v[154:157], v134, s[32:33]
	v_mfma_f32_16x16x32_bf16 v[70:73], v[158:161], v[110:113], v[70:73]
	v_mfma_f32_16x16x32_bf16 v[46:49], v[158:161], v[114:117], v[46:49]
	v_mfma_f32_16x16x32_bf16 v[18:21], v[158:161], v[118:121], v[18:21]
	s_add_u32 s32, s32, 0x400
	s_addc_u32 s33, s33, 0
	global_load_dwordx4 v[158:161], v134, s[32:33]
	v_mfma_f32_16x16x32_bf16 v[66:69], v[162:165], v[110:113], v[66:69]
	v_mfma_f32_16x16x32_bf16 v[42:45], v[162:165], v[114:117], v[42:45]
	v_mfma_f32_16x16x32_bf16 v[14:17], v[162:165], v[118:121], v[14:17]
	s_add_u32 s32, s32, 0x400
	s_addc_u32 s33, s33, 0
	global_load_dwordx4 v[162:165], v134, s[32:33]
	s_waitcnt vmcnt(19)
	v_mfma_f32_16x16x32_bf16 v[78:81], v[172:175], v[110:113], v[78:81]
	v_mfma_f32_16x16x32_bf16 v[50:53], v[172:175], v[114:117], v[50:53]
	v_mfma_f32_16x16x32_bf16 v[22:25], v[172:175], v[118:121], v[22:25]
	s_add_u32 s32, s32, 0x400
	s_addc_u32 s33, s33, 0
	global_load_dwordx4 v[172:175], v134, s[32:33]
	s_waitcnt vmcnt(19)
	v_mfma_f32_16x16x32_bf16 v[82:85], v[176:179], v[110:113], v[82:85]
	v_mfma_f32_16x16x32_bf16 v[58:61], v[176:179], v[114:117], v[58:61]
	v_mfma_f32_16x16x32_bf16 v[30:33], v[176:179], v[118:121], v[30:33]
	s_add_u32 s32, s32, 0x400
	s_addc_u32 s33, s33, 0
	global_load_dwordx4 v[176:179], v134, s[32:33]
	s_waitcnt vmcnt(19)
	v_mfma_f32_16x16x32_bf16 v[86:89], v[180:183], v[110:113], v[86:89]
	v_mfma_f32_16x16x32_bf16 v[54:57], v[180:183], v[114:117], v[54:57]
	v_mfma_f32_16x16x32_bf16 v[26:29], v[180:183], v[118:121], v[26:29]
	s_add_u32 s32, s32, 0x400
	s_addc_u32 s33, s33, 0
	global_load_dwordx4 v[180:183], v134, s[32:33]
	s_waitcnt vmcnt(19)
	v_mfma_f32_16x16x32_bf16 v[94:97], v[122:125], v[110:113], v[94:97]
	v_mfma_f32_16x16x32_bf16 v[62:65], v[122:125], v[114:117], v[62:65]
	v_mfma_f32_16x16x32_bf16 v[34:37], v[122:125], v[118:121], v[34:37]
	s_waitcnt vmcnt(18)
	v_mfma_f32_16x16x32_bf16 v[98:101], v[126:129], v[110:113], v[98:101]
	v_mfma_f32_16x16x32_bf16 v[74:77], v[126:129], v[114:117], v[74:77]
	v_mfma_f32_16x16x32_bf16 v[38:41], v[126:129], v[118:121], v[38:41]
	s_waitcnt vmcnt(17)
	v_mfma_f32_16x16x32_bf16 v[106:109], v[138:141], v[110:113], v[106:109]
	v_mfma_f32_16x16x32_bf16 v[102:105], v[138:141], v[114:117], v[102:105]
	v_mfma_f32_16x16x32_bf16 v[90:93], v[138:141], v[118:121], v[90:93]
	s_waitcnt vmcnt(6)
	v_cvt_pk_bf16_f32 v110, v166, v184
	v_cvt_pk_bf16_f32 v111, v188, v192
	v_cvt_pk_bf16_f32 v112, v214, v218
	v_cvt_pk_bf16_f32 v113, v228, v232
	v_cvt_pk_bf16_f32 v114, v167, v185
	v_cvt_pk_bf16_f32 v115, v189, v193
	v_cvt_pk_bf16_f32 v116, v215, v219
	v_cvt_pk_bf16_f32 v117, v229, v233
	v_cvt_pk_bf16_f32 v118, v168, v186
	v_cvt_pk_bf16_f32 v119, v190, v194
	v_cvt_pk_bf16_f32 v120, v216, v220
	v_cvt_pk_bf16_f32 v121, v230, v234
	s_nop 1
	v_mfma_f32_16x16x32_bf16 v[10:13], v[142:145], v[110:113], v[10:13]
	v_mfma_f32_16x16x32_bf16 v[6:9], v[142:145], v[114:117], v[6:9]
	v_mfma_f32_16x16x32_bf16 v[2:5], v[142:145], v[118:121], v[2:5]
	v_mfma_f32_16x16x32_bf16 v[70:73], v[146:149], v[110:113], v[70:73]
	v_mfma_f32_16x16x32_bf16 v[46:49], v[146:149], v[114:117], v[46:49]
	v_mfma_f32_16x16x32_bf16 v[18:21], v[146:149], v[118:121], v[18:21]
	v_mfma_f32_16x16x32_bf16 v[66:69], v[150:153], v[110:113], v[66:69]
	v_mfma_f32_16x16x32_bf16 v[42:45], v[150:153], v[114:117], v[42:45]
	v_mfma_f32_16x16x32_bf16 v[14:17], v[150:153], v[118:121], v[14:17]
	s_waitcnt vmcnt(5)
	v_mfma_f32_16x16x32_bf16 v[78:81], v[154:157], v[110:113], v[78:81]
	v_mfma_f32_16x16x32_bf16 v[50:53], v[154:157], v[114:117], v[50:53]
	v_mfma_f32_16x16x32_bf16 v[22:25], v[154:157], v[118:121], v[22:25]
	s_waitcnt vmcnt(4)
	v_mfma_f32_16x16x32_bf16 v[82:85], v[158:161], v[110:113], v[82:85]
	v_mfma_f32_16x16x32_bf16 v[58:61], v[158:161], v[114:117], v[58:61]
	v_mfma_f32_16x16x32_bf16 v[30:33], v[158:161], v[118:121], v[30:33]
	s_waitcnt vmcnt(3)
	v_mfma_f32_16x16x32_bf16 v[86:89], v[162:165], v[110:113], v[86:89]
	v_mfma_f32_16x16x32_bf16 v[54:57], v[162:165], v[114:117], v[54:57]
	v_mfma_f32_16x16x32_bf16 v[26:29], v[162:165], v[118:121], v[26:29]
	s_waitcnt vmcnt(2)
	v_mfma_f32_16x16x32_bf16 v[94:97], v[172:175], v[110:113], v[94:97]
	v_mfma_f32_16x16x32_bf16 v[62:65], v[172:175], v[114:117], v[62:65]
	v_mfma_f32_16x16x32_bf16 v[34:37], v[172:175], v[118:121], v[34:37]
	s_waitcnt vmcnt(1)
	v_mfma_f32_16x16x32_bf16 v[98:101], v[176:179], v[110:113], v[98:101]
	v_mfma_f32_16x16x32_bf16 v[74:77], v[176:179], v[114:117], v[74:77]
	v_mfma_f32_16x16x32_bf16 v[38:41], v[176:179], v[118:121], v[38:41]
	s_waitcnt vmcnt(0)
	v_mfma_f32_16x16x32_bf16 v[106:109], v[180:183], v[110:113], v[106:109]
	v_mfma_f32_16x16x32_bf16 v[102:105], v[180:183], v[114:117], v[102:105]
	v_mfma_f32_16x16x32_bf16 v[90:93], v[180:183], v[118:121], v[90:93]
	v_lshrrev_b32_e32 v110, 4, v170
	v_lshlrev_b32_e32 v111, 16, v110
	v_lshlrev_b32_e32 v112, 2, v110
	v_or_b32_e32 v112, 0x82, v112
	v_lshlrev_b32_e32 v113, 2, v110
	v_or_b32_e32 v113, 0x80, v113
	v_lshlrev_b32_e32 v114, 2, v110
	v_or_b32_e32 v114, 0x81, v114
	v_or_b32_e32 v132, 0x4000, v111
	v_or_b32_e32 v134, 0x8000, v111
	v_or_b32_e32 v136, 0xc000, v111
	v_or_b32_e32 v138, 0x40000, v111
	v_or_b32_e32 v140, 0x44000, v111
	v_or_b32_e32 v142, 0x48000, v111
	v_or_b32_e32 v144, 0x4c000, v111
	v_or_b32_e32 v146, 0x80000, v111
	v_or_b32_e32 v148, 0x84000, v111
	v_or_b32_e32 v150, 0x88000, v111
	v_or_b32_e32 v152, 0x8c000, v111
	v_or_b32_e32 v154, 0xc0000, v111
	v_or_b32_e32 v156, 0xc4000, v111
	v_or_b32_e32 v158, 0xc8000, v111
	v_or_b32_e32 v160, 0xcc000, v111
	v_or_b32_e32 v162, 0x100000, v111
	v_or_b32_e32 v164, 0x104000, v111
	v_or_b32_e32 v166, 0x108000, v111
	v_or_b32_e32 v168, 0x10c000, v111
	v_or_b32_e32 v172, 0x140000, v111
	v_or_b32_e32 v174, 0x144000, v111
	v_or_b32_e32 v176, 0x148000, v111
	v_or_b32_e32 v178, 0x14c000, v111
	v_or_b32_e32 v180, 0x180000, v111
	v_or_b32_e32 v182, 0x184000, v111
	v_or_b32_e32 v184, 0x188000, v111
	v_or_b32_e32 v186, 0x18c000, v111
	v_or_b32_e32 v188, 0x1c0000, v111
	v_or_b32_e32 v190, 0x1c4000, v111
	v_or_b32_e32 v192, 0x1c8000, v111
	v_or_b32_e32 v194, 0x1cc000, v111
	v_lshlrev_b32_e32 v214, 2, v111
	v_add_u32_e32 v173, 0xffff7100, v135
	v_add_u32_e32 v175, 0xffff7200, v135
	v_add_u32_e32 v177, 0xffff7300, v135
	v_add_u32_e32 v179, 0xffff7400, v135
	v_add_u32_e32 v181, 0xffff7500, v135
	v_add_u32_e32 v183, 0xffff7600, v135
	v_add_u32_e32 v185, 0xffff7700, v135
	v_add_u32_e32 v187, 0xffff7800, v135
	v_add_u32_e32 v189, 0xffff7900, v135
	v_add_u32_e32 v191, 0xffff7a00, v135
	v_add_u32_e32 v193, 0xffff7b00, v135
	v_add_u32_e32 v195, 0xffff7c00, v135
	v_add_u32_e32 v217, 0xffff7d00, v135
	v_add_u32_e32 v219, 0xffff7e00, v135
	v_add_u32_e32 v221, 0xffff7f00, v135
	v_add_u32_e32 v171, 0xffff8000, v135
	v_add_u32_e32 v251, 0xffff8100, v135
	v_add_u32_e32 v252, 0xffff8200, v135
	v_add_u32_e32 v253, 0xffff8300, v135
	v_add_u32_e32 v254, 0xffff8400, v135
	v_add_u32_e32 v139, 0xffff8500, v135
	v_add_u32_e32 v141, 0xffff8600, v135
	v_add_u32_e32 v143, 0xffff8700, v135
	v_add_u32_e32 v145, 0xffff8800, v135
	v_add_u32_e32 v147, 0xffff8900, v135
	v_add_u32_e32 v149, 0xffff8a00, v135
	v_add_u32_e32 v151, 0xffff8b00, v135
	v_add_u32_e32 v153, 0xffff8c00, v135
	v_add_u32_e32 v155, 0xffff8d00, v135
	v_add_u32_e32 v157, 0xffff8e00, v135
	v_add_u32_e32 v159, 0xffff8f00, v135
	v_add_u32_e32 v161, 0xffff9000, v135
	v_add_u32_e32 v163, 0xffff9100, v135
	v_add_u32_e32 v165, 0xffff9200, v135
	v_add_u32_e32 v167, 0xffff9300, v135
	v_lshlrev_b32_e32 v216, 14, v113
	v_lshlrev_b32_e32 v218, 14, v114
	v_lshlrev_b32_e32 v220, 14, v112
	s_and_b64 vcc, exec, s[10:11]
	s_cbranch_vccz .LBB0_33
	v_add_u32_e32 v110, 0xfffe5000, v135
	ds_write_b32 v110, v10
	v_add_u32_e32 v110, 0xfffe5100, v135
	ds_write_b32 v110, v11
	v_add_u32_e32 v110, 0xfffe5200, v135
	ds_write_b32 v110, v12
	v_add_u32_e32 v110, 0xfffe5300, v135
	ds_write_b32 v110, v13
	v_add_u32_e32 v110, 0xfffe5400, v135
	ds_write_b32 v110, v6
	v_add_u32_e32 v110, 0xfffe5500, v135
	ds_write_b32 v110, v7
	v_add_u32_e32 v110, 0xfffe5600, v135
	ds_write_b32 v110, v8
	v_add_u32_e32 v110, 0xfffe5700, v135
	ds_write_b32 v110, v9
	v_add_u32_e32 v110, 0xfffe5800, v135
	ds_write_b32 v110, v2
	v_add_u32_e32 v110, 0xfffe5900, v135
	ds_write_b32 v110, v3
	v_add_u32_e32 v110, 0xfffe5a00, v135
	ds_write_b32 v110, v4
	v_add_u32_e32 v110, 0xfffe5b00, v135
	ds_write_b32 v110, v5
	v_add_u32_e32 v110, 0xfffe5c00, v135
	ds_write_b32 v110, v70
	v_add_u32_e32 v110, 0xfffe5d00, v135
	ds_write_b32 v110, v71
	v_add_u32_e32 v110, 0xfffe5e00, v135
	ds_write_b32 v110, v72
	v_add_u32_e32 v110, 0xfffe5f00, v135
	ds_write_b32 v110, v73
	v_add_u32_e32 v110, 0xfffe6000, v135
	ds_write_b32 v110, v46
	v_add_u32_e32 v110, 0xfffe6100, v135
	ds_write_b32 v110, v47
	v_add_u32_e32 v110, 0xfffe6200, v135
	ds_write_b32 v110, v48
	v_add_u32_e32 v110, 0xfffe6300, v135
	ds_write_b32 v110, v49
	v_add_u32_e32 v110, 0xfffe6400, v135
	ds_write_b32 v110, v18
	v_add_u32_e32 v110, 0xfffe6500, v135
	ds_write_b32 v110, v19
	v_add_u32_e32 v110, 0xfffe6600, v135
	ds_write_b32 v110, v20
	v_add_u32_e32 v110, 0xfffe6700, v135
	ds_write_b32 v110, v21
	v_add_u32_e32 v110, 0xfffe6800, v135
	ds_write_b32 v110, v66
	v_add_u32_e32 v110, 0xfffe6900, v135
	ds_write_b32 v110, v67
	v_add_u32_e32 v110, 0xfffe6a00, v135
	ds_write_b32 v110, v68
	v_add_u32_e32 v110, 0xfffe6b00, v135
	ds_write_b32 v110, v69
	v_add_u32_e32 v110, 0xfffe6c00, v135
	ds_write_b32 v110, v42
	v_add_u32_e32 v110, 0xfffe6d00, v135
	ds_write_b32 v110, v43
	v_add_u32_e32 v110, 0xfffe6e00, v135
	ds_write_b32 v110, v44
	v_add_u32_e32 v110, 0xfffe6f00, v135
	ds_write_b32 v110, v45
	v_add_u32_e32 v110, 0xfffe7000, v135
	ds_write_b32 v110, v14
	v_add_u32_e32 v110, 0xfffe7100, v135
	ds_write_b32 v110, v15
	v_add_u32_e32 v110, 0xfffe7200, v135
	ds_write_b32 v110, v16
	v_add_u32_e32 v110, 0xfffe7300, v135
	ds_write_b32 v110, v17
	v_add_u32_e32 v110, 0xfffe7400, v135
	ds_write_b32 v110, v78
	v_add_u32_e32 v110, 0xfffe7500, v135
	ds_write_b32 v110, v79
	v_add_u32_e32 v110, 0xfffe7600, v135
	ds_write_b32 v110, v80
	v_add_u32_e32 v110, 0xfffe7700, v135
	ds_write_b32 v110, v81
	v_add_u32_e32 v110, 0xfffe7800, v135
	ds_write_b32 v110, v50
	v_add_u32_e32 v110, 0xfffe7900, v135
	ds_write_b32 v110, v51
	v_add_u32_e32 v110, 0xfffe7a00, v135
	ds_write_b32 v110, v52
	v_add_u32_e32 v110, 0xfffe7b00, v135
	ds_write_b32 v110, v53
	v_add_u32_e32 v110, 0xfffe7c00, v135
	ds_write_b32 v110, v22
	v_add_u32_e32 v110, 0xfffe7d00, v135
	ds_write_b32 v110, v23
	v_add_u32_e32 v110, 0xfffe7e00, v135
	ds_write_b32 v110, v24
	v_add_u32_e32 v110, 0xfffe7f00, v135
	ds_write_b32 v110, v25
	v_add_u32_e32 v110, 0xfffe8000, v135
	ds_write_b32 v110, v82
	v_add_u32_e32 v110, 0xfffe8100, v135
	ds_write_b32 v110, v83
	v_add_u32_e32 v110, 0xfffe8200, v135
	ds_write_b32 v110, v84
	v_add_u32_e32 v110, 0xfffe8300, v135
	ds_write_b32 v110, v85
	v_add_u32_e32 v110, 0xfffe8400, v135
	ds_write_b32 v110, v58
	v_add_u32_e32 v110, 0xfffe8500, v135
	ds_write_b32 v110, v59
	v_add_u32_e32 v110, 0xfffe8600, v135
	ds_write_b32 v110, v60
	v_add_u32_e32 v110, 0xfffe8700, v135
	ds_write_b32 v110, v61
	v_add_u32_e32 v110, 0xfffe8800, v135
	ds_write_b32 v110, v30
	v_add_u32_e32 v110, 0xfffe8900, v135
	ds_write_b32 v110, v31
	v_add_u32_e32 v110, 0xfffe8a00, v135
	ds_write_b32 v110, v32
	v_add_u32_e32 v110, 0xfffe8b00, v135
	ds_write_b32 v110, v33
	v_add_u32_e32 v110, 0xfffe8c00, v135
	ds_write_b32 v110, v86
	v_add_u32_e32 v110, 0xfffe8d00, v135
	ds_write_b32 v110, v87
	v_add_u32_e32 v110, 0xfffe8e00, v135
	ds_write_b32 v110, v88
	v_add_u32_e32 v110, 0xfffe8f00, v135
	ds_write_b32 v110, v89
	v_add_u32_e32 v110, 0xfffe9000, v135
	ds_write_b32 v110, v54
	v_add_u32_e32 v110, 0xfffe9100, v135
	ds_write_b32 v110, v55
	v_add_u32_e32 v110, 0xfffe9200, v135
	ds_write_b32 v110, v56
	v_add_u32_e32 v110, 0xfffe9300, v135
	ds_write_b32 v110, v57
	v_add_u32_e32 v110, 0xfffe9400, v135
	ds_write_b32 v110, v26
	v_add_u32_e32 v110, 0xfffe9500, v135
	ds_write_b32 v110, v27
	v_add_u32_e32 v110, 0xfffe9600, v135
	ds_write_b32 v110, v28
	v_add_u32_e32 v110, 0xfffe9700, v135
	ds_write_b32 v110, v29
	v_add_u32_e32 v110, 0xfffe9800, v135
	ds_write_b32 v110, v94
	v_add_u32_e32 v110, 0xfffe9900, v135
	ds_write_b32 v110, v95
	v_add_u32_e32 v110, 0xfffe9a00, v135
	ds_write_b32 v110, v96
	v_add_u32_e32 v110, 0xfffe9b00, v135
	ds_write_b32 v110, v97
	v_add_u32_e32 v110, 0xfffe9c00, v135
	ds_write_b32 v110, v62
	v_add_u32_e32 v110, 0xfffe9d00, v135
	ds_write_b32 v110, v63
	v_add_u32_e32 v110, 0xfffe9e00, v135
	ds_write_b32 v110, v64
	v_add_u32_e32 v110, 0xfffe9f00, v135
	ds_write_b32 v110, v65
	v_add_u32_e32 v110, 0xfffea000, v135
	ds_write_b32 v110, v34
	v_add_u32_e32 v110, 0xfffea100, v135
	ds_write_b32 v110, v35
	v_add_u32_e32 v110, 0xfffea200, v135
	ds_write_b32 v110, v36
	v_add_u32_e32 v110, 0xfffea300, v135
	ds_write_b32 v110, v37
	v_add_u32_e32 v110, 0xfffea400, v135
	ds_write_b32 v110, v98
	v_add_u32_e32 v110, 0xfffea500, v135
	ds_write_b32 v110, v99
	v_add_u32_e32 v110, 0xfffea600, v135
	ds_write_b32 v110, v100
	v_add_u32_e32 v110, 0xfffea700, v135
	ds_write_b32 v110, v101
	v_add_u32_e32 v110, 0xfffea800, v135
	ds_write_b32 v110, v74
	v_add_u32_e32 v110, 0xfffea900, v135
	ds_write_b32 v110, v75
	v_add_u32_e32 v110, 0xfffeaa00, v135
	ds_write_b32 v110, v76
	v_add_u32_e32 v110, 0xfffeab00, v135
	ds_write_b32 v110, v77
	v_add_u32_e32 v110, 0xfffeac00, v135
	ds_write_b32 v110, v38
	v_add_u32_e32 v110, 0xfffead00, v135
	ds_write_b32 v110, v39
	v_add_u32_e32 v110, 0xfffeae00, v135
	ds_write_b32 v110, v40
	v_add_u32_e32 v110, 0xfffeaf00, v135
	ds_write_b32 v110, v41
	v_add_u32_e32 v110, 0xfffeb000, v135
	ds_write_b32 v110, v106
	v_add_u32_e32 v110, 0xfffeb100, v135
	ds_write_b32 v110, v107
	v_add_u32_e32 v110, 0xfffeb200, v135
	ds_write_b32 v110, v108
	v_add_u32_e32 v110, 0xfffeb300, v135
	ds_write_b32 v110, v109
	v_add_u32_e32 v110, 0xfffeb400, v135
	ds_write_b32 v110, v102
	v_add_u32_e32 v110, 0xfffeb500, v135
	ds_write_b32 v110, v103
	v_add_u32_e32 v110, 0xfffeb600, v135
	ds_write_b32 v110, v104
	v_add_u32_e32 v110, 0xfffeb700, v135
	ds_write_b32 v110, v105
	v_add_u32_e32 v110, 0xfffeb800, v135
	ds_write_b32 v110, v90
	v_add_u32_e32 v110, 0xfffeb900, v135
	ds_write_b32 v110, v91
	v_add_u32_e32 v110, 0xfffeba00, v135
	ds_write_b32 v110, v92
	v_add_u32_e32 v110, 0xfffebb00, v135
	ds_write_b32 v110, v93

.LBB0_82:
	v_add_u32_e32 v130, s63, v133
	v_mad_u64_u32 v[236:237], s[0:1], v130, s69, v[226:227]
	global_load_dwordx3 v[158:160], v[236:237], off nt
	v_add_u32_e32 v132, 1, v130
	v_mad_u64_u32 v[236:237], s[0:1], v132, s69, v[226:227]
	global_load_dwordx3 v[202:204], v[236:237], off nt
	v_add_u32_e32 v132, 2, v130
	v_mad_u64_u32 v[236:237], s[0:1], v132, s69, v[226:227]
	global_load_dwordx3 v[206:208], v[236:237], off nt
	v_add_u32_e32 v132, 3, v130
	v_mad_u64_u32 v[236:237], s[0:1], v132, s69, v[226:227]
	global_load_dwordx3 v[210:212], v[236:237], off nt
	v_add_u32_e32 v132, 4, v130
	v_mad_u64_u32 v[236:237], s[0:1], v132, s69, v[226:227]
	global_load_dwordx3 v[214:216], v[236:237], off nt
	v_add_u32_e32 v132, 5, v130
	v_mad_u64_u32 v[236:237], s[0:1], v132, s69, v[226:227]
	global_load_dwordx3 v[218:220], v[236:237], off nt
	v_add_u32_e32 v132, 6, v130
	v_mad_u64_u32 v[236:237], s[0:1], v132, s69, v[226:227]
	global_load_dwordx3 v[228:230], v[236:237], off nt
	v_add_u32_e32 v132, 7, v130
	v_mad_u64_u32 v[236:237], s[0:1], v132, s69, v[226:227]
	global_load_dwordx3 v[232:234], v[236:237], off nt
	v_readlane_b32 s74, v255, 5
	s_mul_i32 s73, s74, 0x12000
	s_add_u32 s32, s70, 0x7800000
	s_addc_u32 s33, s71, 0
	s_add_u32 s32, s32, s73
	s_addc_u32 s33, s33, 0
	v_lshlrev_b32_e32 v134, 4, v170
	s_cmp_lg_u32 s74, 0
	s_cbranch_scc1 .Lp0cb_even_sync
	v_mov_b32_e32 v136, 0x3f00
	s_mov_b32 s73, 0

.Lp0cb_even_sync:
	s_barrier
	global_load_dwordx4 v[122:125], v134, s[32:33]
	s_add_u32 s32, s32, 0x400
	s_addc_u32 s33, s33, 0
	global_load_dwordx4 v[126:129], v134, s[32:33]
	s_add_u32 s32, s32, 0x400
	s_addc_u32 s33, s33, 0
	global_load_dwordx4 v[138:141], v134, s[32:33]
	s_add_u32 s32, s32, 0x400
	s_addc_u32 s33, s33, 0
	global_load_dwordx4 v[142:145], v134, s[32:33]
	s_add_u32 s32, s32, 0x400
	s_addc_u32 s33, s33, 0
	global_load_dwordx4 v[146:149], v134, s[32:33]
	s_add_u32 s32, s32, 0x400
	s_addc_u32 s33, s33, 0
	global_load_dwordx4 v[150:153], v134, s[32:33]
	s_add_u32 s32, s32, 0x400
	s_addc_u32 s33, s33, 0
	global_load_dwordx4 v[154:157], v134, s[32:33]
	s_add_u32 s32, s32, 0x400
	s_addc_u32 s33, s33, 0
	global_load_dwordx4 v[182:185], v134, s[32:33]
	s_add_u32 s32, s32, 0x400
	s_addc_u32 s33, s33, 0
	global_load_dwordx4 v[186:189], v134, s[32:33]
	s_add_u32 s32, s32, 0x400
	s_addc_u32 s33, s33, 0
	global_load_dwordx4 v[190:193], v134, s[32:33]
	s_add_u32 s32, s32, 0x400
	s_addc_u32 s33, s33, 0
	global_load_dwordx4 v[194:197], v134, s[32:33]
	s_add_u32 s32, s32, 0x400
	s_addc_u32 s33, s33, 0
	global_load_dwordx4 v[198:201], v134, s[32:33]
	s_add_i32 s63, s63, 256
	s_waitcnt vmcnt(12)
	v_cvt_pk_bf16_f32 v110, v158, v202
	v_cvt_pk_bf16_f32 v111, v206, v210
	v_cvt_pk_bf16_f32 v112, v214, v218
	v_cvt_pk_bf16_f32 v113, v228, v232
	v_cvt_pk_bf16_f32 v114, v159, v203
	v_cvt_pk_bf16_f32 v115, v207, v211
	v_cvt_pk_bf16_f32 v116, v215, v219
	v_cvt_pk_bf16_f32 v117, v229, v233
	v_cvt_pk_bf16_f32 v118, v160, v204
	v_cvt_pk_bf16_f32 v119, v208, v212
	v_cvt_pk_bf16_f32 v120, v216, v220
	v_cvt_pk_bf16_f32 v121, v230, v234
	v_add_u32_e32 v132, 32, v130
	v_mad_u64_u32 v[236:237], s[0:1], v132, s69, v[226:227]
	global_load_dwordx3 v[158:160], v[236:237], off nt
	v_add_u32_e32 v132, 33, v130
	v_mad_u64_u32 v[236:237], s[0:1], v132, s69, v[226:227]
	global_load_dwordx3 v[202:204], v[236:237], off nt
	v_add_u32_e32 v132, 34, v130
	v_mad_u64_u32 v[236:237], s[0:1], v132, s69, v[226:227]
	global_load_dwordx3 v[206:208], v[236:237], off nt
	v_add_u32_e32 v132, 35, v130
	v_mad_u64_u32 v[236:237], s[0:1], v132, s69, v[226:227]
	global_load_dwordx3 v[210:212], v[236:237], off nt
	v_add_u32_e32 v132, 36, v130
	v_mad_u64_u32 v[236:237], s[0:1], v132, s69, v[226:227]
	global_load_dwordx3 v[214:216], v[236:237], off nt
	v_add_u32_e32 v132, 37, v130
	v_mad_u64_u32 v[236:237], s[0:1], v132, s69, v[226:227]
	global_load_dwordx3 v[218:220], v[236:237], off nt
	v_add_u32_e32 v132, 38, v130
	v_mad_u64_u32 v[236:237], s[0:1], v132, s69, v[226:227]
	global_load_dwordx3 v[228:230], v[236:237], off nt
	v_add_u32_e32 v132, 39, v130
	v_mad_u64_u32 v[236:237], s[0:1], v132, s69, v[226:227]
	global_load_dwordx3 v[232:234], v[236:237], off nt
	s_waitcnt vmcnt(19)
	s_nop 1
	v_mfma_f32_16x16x32_bf16 v[18:21], v[122:125], v[110:113], v[18:21]
	v_mfma_f32_16x16x32_bf16 v[6:9], v[122:125], v[114:117], v[6:9]
	v_mfma_f32_16x16x32_bf16 v[2:5], v[122:125], v[118:121], v[2:5]
	s_add_u32 s32, s32, 0x400
	s_addc_u32 s33, s33, 0
	global_load_dwordx4 v[122:125], v134, s[32:33]
	s_waitcnt vmcnt(19)
	v_mfma_f32_16x16x32_bf16 v[70:73], v[126:129], v[110:113], v[70:73]
	v_mfma_f32_16x16x32_bf16 v[46:49], v[126:129], v[114:117], v[46:49]
	v_mfma_f32_16x16x32_bf16 v[10:13], v[126:129], v[118:121], v[10:13]
	s_add_u32 s32, s32, 0x400
	s_addc_u32 s33, s33, 0
	global_load_dwordx4 v[126:129], v134, s[32:33]
	s_waitcnt vmcnt(19)
	v_mfma_f32_16x16x32_bf16 v[66:69], v[138:141], v[110:113], v[66:69]
	v_mfma_f32_16x16x32_bf16 v[38:41], v[138:141], v[114:117], v[38:41]
	v_mfma_f32_16x16x32_bf16 v[14:17], v[138:141], v[118:121], v[14:17]
	s_add_u32 s32, s32, 0x400
	s_addc_u32 s33, s33, 0
	global_load_dwordx4 v[138:141], v134, s[32:33]
	s_waitcnt vmcnt(19)
	v_mfma_f32_16x16x32_bf16 v[78:81], v[142:145], v[110:113], v[78:81]
	v_mfma_f32_16x16x32_bf16 v[50:53], v[142:145], v[114:117], v[50:53]
	v_mfma_f32_16x16x32_bf16 v[22:25], v[142:145], v[118:121], v[22:25]
	s_add_u32 s32, s32, 0x400
	s_addc_u32 s33, s33, 0
	global_load_dwordx4 v[142:145], v134, s[32:33]
	s_waitcnt vmcnt(19)
	v_mfma_f32_16x16x32_bf16 v[82:85], v[146:149], v[110:113], v[82:85]
	v_mfma_f32_16x16x32_bf16 v[58:61], v[146:149], v[114:117], v[58:61]
	v_mfma_f32_16x16x32_bf16 v[30:33], v[146:149], v[118:121], v[30:33]
	s_add_u32 s32, s32, 0x400
	s_addc_u32 s33, s33, 0
	global_load_dwordx4 v[146:149], v134, s[32:33]
	s_waitcnt vmcnt(19)
	v_mfma_f32_16x16x32_bf16 v[86:89], v[150:153], v[110:113], v[86:89]
	v_mfma_f32_16x16x32_bf16 v[54:57], v[150:153], v[114:117], v[54:57]
	v_mfma_f32_16x16x32_bf16 v[26:29], v[150:153], v[118:121], v[26:29]
	s_add_u32 s32, s32, 0x400
	s_addc_u32 s33, s33, 0
	global_load_dwordx4 v[150:153], v134, s[32:33]
	s_waitcnt vmcnt(19)
	v_mfma_f32_16x16x32_bf16 v[94:97], v[154:157], v[110:113], v[94:97]
	v_mfma_f32_16x16x32_bf16 v[62:65], v[154:157], v[114:117], v[62:65]
	v_mfma_f32_16x16x32_bf16 v[34:37], v[154:157], v[118:121], v[34:37]
	s_add_u32 s32, s32, 0x400
	s_addc_u32 s33, s33, 0
	global_load_dwordx4 v[154:157], v134, s[32:33]
	s_waitcnt vmcnt(19)
	v_mfma_f32_16x16x32_bf16 v[98:101], v[182:185], v[110:113], v[98:101]
	v_mfma_f32_16x16x32_bf16 v[74:77], v[182:185], v[114:117], v[74:77]
	v_mfma_f32_16x16x32_bf16 v[42:45], v[182:185], v[118:121], v[42:45]
	s_add_u32 s32, s32, 0x400
	s_addc_u32 s33, s33, 0
	global_load_dwordx4 v[182:185], v134, s[32:33]
	s_waitcnt vmcnt(19)
	v_mfma_f32_16x16x32_bf16 v[106:109], v[186:189], v[110:113], v[106:109]
	v_mfma_f32_16x16x32_bf16 v[102:105], v[186:189], v[114:117], v[102:105]
	v_mfma_f32_16x16x32_bf16 v[90:93], v[186:189], v[118:121], v[90:93]
	s_add_u32 s32, s32, 0x400
	s_addc_u32 s33, s33, 0
	global_load_dwordx4 v[186:189], v134, s[32:33]
	s_waitcnt vmcnt(9)
	v_cvt_pk_bf16_f32 v110, v158, v202
	v_cvt_pk_bf16_f32 v111, v206, v210
	v_cvt_pk_bf16_f32 v112, v214, v218
	v_cvt_pk_bf16_f32 v113, v228, v232
	v_cvt_pk_bf16_f32 v114, v159, v203
	v_cvt_pk_bf16_f32 v115, v207, v211
	v_cvt_pk_bf16_f32 v116, v215, v219
	v_cvt_pk_bf16_f32 v117, v229, v233
	v_cvt_pk_bf16_f32 v118, v160, v204
	v_cvt_pk_bf16_f32 v119, v208, v212
	v_cvt_pk_bf16_f32 v120, v216, v220
	v_cvt_pk_bf16_f32 v121, v230, v234
	v_add_u32_e32 v132, 64, v130
	v_mad_u64_u32 v[236:237], s[0:1], v132, s69, v[226:227]
	global_load_dwordx3 v[158:160], v[236:237], off nt
	v_add_u32_e32 v132, 65, v130
	v_mad_u64_u32 v[236:237], s[0:1], v132, s69, v[226:227]
	global_load_dwordx3 v[202:204], v[236:237], off nt
	v_add_u32_e32 v132, 66, v130
	v_mad_u64_u32 v[236:237], s[0:1], v132, s69, v[226:227]
	global_load_dwordx3 v[206:208], v[236:237], off nt
	v_add_u32_e32 v132, 67, v130
	v_mad_u64_u32 v[236:237], s[0:1], v132, s69, v[226:227]
	global_load_dwordx3 v[210:212], v[236:237], off nt
	v_add_u32_e32 v132, 68, v130
	v_mad_u64_u32 v[236:237], s[0:1], v132, s69, v[226:227]
	global_load_dwordx3 v[214:216], v[236:237], off nt
	v_add_u32_e32 v132, 69, v130
	v_mad_u64_u32 v[236:237], s[0:1], v132, s69, v[226:227]
	global_load_dwordx3 v[218:220], v[236:237], off nt
	v_add_u32_e32 v132, 70, v130
	v_mad_u64_u32 v[236:237], s[0:1], v132, s69, v[226:227]
	global_load_dwordx3 v[228:230], v[236:237], off nt
	v_add_u32_e32 v132, 71, v130
	v_mad_u64_u32 v[236:237], s[0:1], v132, s69, v[226:227]
	global_load_dwordx3 v[232:234], v[236:237], off nt
	s_nop 1
	v_mfma_f32_16x16x32_bf16 v[18:21], v[190:193], v[110:113], v[18:21]
	v_mfma_f32_16x16x32_bf16 v[6:9], v[190:193], v[114:117], v[6:9]
	v_mfma_f32_16x16x32_bf16 v[2:5], v[190:193], v[118:121], v[2:5]
	s_add_u32 s32, s32, 0x400
	s_addc_u32 s33, s33, 0
	global_load_dwordx4 v[190:193], v134, s[32:33]
	v_mfma_f32_16x16x32_bf16 v[70:73], v[194:197], v[110:113], v[70:73]
	v_mfma_f32_16x16x32_bf16 v[46:49], v[194:197], v[114:117], v[46:49]
	v_mfma_f32_16x16x32_bf16 v[10:13], v[194:197], v[118:121], v[10:13]
	s_add_u32 s32, s32, 0x400
	s_addc_u32 s33, s33, 0
	global_load_dwordx4 v[194:197], v134, s[32:33]
	v_mfma_f32_16x16x32_bf16 v[66:69], v[198:201], v[110:113], v[66:69]
	v_mfma_f32_16x16x32_bf16 v[38:41], v[198:201], v[114:117], v[38:41]
	v_mfma_f32_16x16x32_bf16 v[14:17], v[198:201], v[118:121], v[14:17]
	s_add_u32 s32, s32, 0x400
	s_addc_u32 s33, s33, 0
	global_load_dwordx4 v[198:201], v134, s[32:33]
	s_waitcnt vmcnt(19)
	v_mfma_f32_16x16x32_bf16 v[78:81], v[122:125], v[110:113], v[78:81]
	v_mfma_f32_16x16x32_bf16 v[50:53], v[122:125], v[114:117], v[50:53]
	v_mfma_f32_16x16x32_bf16 v[22:25], v[122:125], v[118:121], v[22:25]
	s_add_u32 s32, s32, 0x400
	s_addc_u32 s33, s33, 0
	global_load_dwordx4 v[122:125], v134, s[32:33]
	s_waitcnt vmcnt(19)
	v_mfma_f32_16x16x32_bf16 v[82:85], v[126:129], v[110:113], v[82:85]
	v_mfma_f32_16x16x32_bf16 v[58:61], v[126:129], v[114:117], v[58:61]
	v_mfma_f32_16x16x32_bf16 v[30:33], v[126:129], v[118:121], v[30:33]
	s_add_u32 s32, s32, 0x400
	s_addc_u32 s33, s33, 0
	global_load_dwordx4 v[126:129], v134, s[32:33]
	s_waitcnt vmcnt(19)
	v_mfma_f32_16x16x32_bf16 v[86:89], v[138:141], v[110:113], v[86:89]
	v_mfma_f32_16x16x32_bf16 v[54:57], v[138:141], v[114:117], v[54:57]
	v_mfma_f32_16x16x32_bf16 v[26:29], v[138:141], v[118:121], v[26:29]
	s_add_u32 s32, s32, 0x400
	s_addc_u32 s33, s33, 0
	global_load_dwordx4 v[138:141], v134, s[32:33]
	s_waitcnt vmcnt(19)
	v_mfma_f32_16x16x32_bf16 v[94:97], v[142:145], v[110:113], v[94:97]
	v_mfma_f32_16x16x32_bf16 v[62:65], v[142:145], v[114:117], v[62:65]
	v_mfma_f32_16x16x32_bf16 v[34:37], v[142:145], v[118:121], v[34:37]
	s_add_u32 s32, s32, 0x400
	s_addc_u32 s33, s33, 0
	global_load_dwordx4 v[142:145], v134, s[32:33]
	s_waitcnt vmcnt(19)
	v_mfma_f32_16x16x32_bf16 v[98:101], v[146:149], v[110:113], v[98:101]
	v_mfma_f32_16x16x32_bf16 v[74:77], v[146:149], v[114:117], v[74:77]
	v_mfma_f32_16x16x32_bf16 v[42:45], v[146:149], v[118:121], v[42:45]
	s_add_u32 s32, s32, 0x400
	s_addc_u32 s33, s33, 0
	global_load_dwordx4 v[146:149], v134, s[32:33]
	s_waitcnt vmcnt(19)
	v_mfma_f32_16x16x32_bf16 v[106:109], v[150:153], v[110:113], v[106:109]
	v_mfma_f32_16x16x32_bf16 v[102:105], v[150:153], v[114:117], v[102:105]
	v_mfma_f32_16x16x32_bf16 v[90:93], v[150:153], v[118:121], v[90:93]
	s_add_u32 s32, s32, 0x400
	s_addc_u32 s33, s33, 0
	global_load_dwordx4 v[150:153], v134, s[32:33]
	s_waitcnt vmcnt(9)
	v_cvt_pk_bf16_f32 v110, v158, v202
	v_cvt_pk_bf16_f32 v111, v206, v210
	v_cvt_pk_bf16_f32 v112, v214, v218
	v_cvt_pk_bf16_f32 v113, v228, v232
	v_cvt_pk_bf16_f32 v114, v159, v203
	v_cvt_pk_bf16_f32 v115, v207, v211
	v_cvt_pk_bf16_f32 v116, v215, v219
	v_cvt_pk_bf16_f32 v117, v229, v233
	v_cvt_pk_bf16_f32 v118, v160, v204
	v_cvt_pk_bf16_f32 v119, v208, v212
	v_cvt_pk_bf16_f32 v120, v216, v220
	v_cvt_pk_bf16_f32 v121, v230, v234
	v_add_u32_e32 v132, 96, v130
	v_mad_u64_u32 v[236:237], s[0:1], v132, s69, v[226:227]
	global_load_dwordx3 v[158:160], v[236:237], off nt
	v_add_u32_e32 v132, 97, v130
	v_mad_u64_u32 v[236:237], s[0:1], v132, s69, v[226:227]
	global_load_dwordx3 v[202:204], v[236:237], off nt
	v_add_u32_e32 v132, 98, v130
	v_mad_u64_u32 v[236:237], s[0:1], v132, s69, v[226:227]
	global_load_dwordx3 v[206:208], v[236:237], off nt
	v_add_u32_e32 v132, 99, v130
	v_mad_u64_u32 v[236:237], s[0:1], v132, s69, v[226:227]
	global_load_dwordx3 v[210:212], v[236:237], off nt
	v_add_u32_e32 v132, 100, v130
	v_mad_u64_u32 v[236:237], s[0:1], v132, s69, v[226:227]
	global_load_dwordx3 v[214:216], v[236:237], off nt
	v_add_u32_e32 v132, 101, v130
	v_mad_u64_u32 v[236:237], s[0:1], v132, s69, v[226:227]
	global_load_dwordx3 v[218:220], v[236:237], off nt
	v_add_u32_e32 v132, 102, v130
	v_mad_u64_u32 v[236:237], s[0:1], v132, s69, v[226:227]
	global_load_dwordx3 v[228:230], v[236:237], off nt
	v_add_u32_e32 v132, 103, v130
	v_mad_u64_u32 v[236:237], s[0:1], v132, s69, v[226:227]
	global_load_dwordx3 v[232:234], v[236:237], off nt
	s_nop 1
	v_mfma_f32_16x16x32_bf16 v[18:21], v[154:157], v[110:113], v[18:21]
	v_mfma_f32_16x16x32_bf16 v[6:9], v[154:157], v[114:117], v[6:9]
	v_mfma_f32_16x16x32_bf16 v[2:5], v[154:157], v[118:121], v[2:5]
	s_add_u32 s32, s32, 0x400
	s_addc_u32 s33, s33, 0
	global_load_dwordx4 v[154:157], v134, s[32:33]
	v_mfma_f32_16x16x32_bf16 v[70:73], v[182:185], v[110:113], v[70:73]
	v_mfma_f32_16x16x32_bf16 v[46:49], v[182:185], v[114:117], v[46:49]
	v_mfma_f32_16x16x32_bf16 v[10:13], v[182:185], v[118:121], v[10:13]
	s_add_u32 s32, s32, 0x400
	s_addc_u32 s33, s33, 0
	global_load_dwordx4 v[182:185], v134, s[32:33]
	v_mfma_f32_16x16x32_bf16 v[66:69], v[186:189], v[110:113], v[66:69]
	v_mfma_f32_16x16x32_bf16 v[38:41], v[186:189], v[114:117], v[38:41]
	v_mfma_f32_16x16x32_bf16 v[14:17], v[186:189], v[118:121], v[14:17]
	s_add_u32 s32, s32, 0x400
	s_addc_u32 s33, s33, 0
	global_load_dwordx4 v[186:189], v134, s[32:33]
	s_waitcnt vmcnt(19)
	v_mfma_f32_16x16x32_bf16 v[78:81], v[190:193], v[110:113], v[78:81]
	v_mfma_f32_16x16x32_bf16 v[50:53], v[190:193], v[114:117], v[50:53]
	v_mfma_f32_16x16x32_bf16 v[22:25], v[190:193], v[118:121], v[22:25]
	s_add_u32 s32, s32, 0x400
	s_addc_u32 s33, s33, 0
	global_load_dwordx4 v[190:193], v134, s[32:33]
	s_waitcnt vmcnt(19)
	v_mfma_f32_16x16x32_bf16 v[82:85], v[194:197], v[110:113], v[82:85]
	v_mfma_f32_16x16x32_bf16 v[58:61], v[194:197], v[114:117], v[58:61]
	v_mfma_f32_16x16x32_bf16 v[30:33], v[194:197], v[118:121], v[30:33]
	s_add_u32 s32, s32, 0x400
	s_addc_u32 s33, s33, 0
	global_load_dwordx4 v[194:197], v134, s[32:33]
	s_waitcnt vmcnt(19)
	v_mfma_f32_16x16x32_bf16 v[86:89], v[198:201], v[110:113], v[86:89]
	v_mfma_f32_16x16x32_bf16 v[54:57], v[198:201], v[114:117], v[54:57]
	v_mfma_f32_16x16x32_bf16 v[26:29], v[198:201], v[118:121], v[26:29]
	s_add_u32 s32, s32, 0x400
	s_addc_u32 s33, s33, 0
	global_load_dwordx4 v[198:201], v134, s[32:33]
	s_waitcnt vmcnt(19)
	v_mfma_f32_16x16x32_bf16 v[94:97], v[122:125], v[110:113], v[94:97]
	v_mfma_f32_16x16x32_bf16 v[62:65], v[122:125], v[114:117], v[62:65]
	v_mfma_f32_16x16x32_bf16 v[34:37], v[122:125], v[118:121], v[34:37]
	s_add_u32 s32, s32, 0x400
	s_addc_u32 s33, s33, 0
	global_load_dwordx4 v[122:125], v134, s[32:33]
	s_waitcnt vmcnt(19)
	v_mfma_f32_16x16x32_bf16 v[98:101], v[126:129], v[110:113], v[98:101]
	v_mfma_f32_16x16x32_bf16 v[74:77], v[126:129], v[114:117], v[74:77]
	v_mfma_f32_16x16x32_bf16 v[42:45], v[126:129], v[118:121], v[42:45]
	s_add_u32 s32, s32, 0x400
	s_addc_u32 s33, s33, 0
	global_load_dwordx4 v[126:129], v134, s[32:33]
	s_waitcnt vmcnt(19)
	v_mfma_f32_16x16x32_bf16 v[106:109], v[138:141], v[110:113], v[106:109]
	v_mfma_f32_16x16x32_bf16 v[102:105], v[138:141], v[114:117], v[102:105]
	v_mfma_f32_16x16x32_bf16 v[90:93], v[138:141], v[118:121], v[90:93]
	s_add_u32 s32, s32, 0x400
	s_addc_u32 s33, s33, 0
	global_load_dwordx4 v[138:141], v134, s[32:33]
	s_waitcnt vmcnt(9)
	v_cvt_pk_bf16_f32 v110, v158, v202
	v_cvt_pk_bf16_f32 v111, v206, v210
	v_cvt_pk_bf16_f32 v112, v214, v218
	v_cvt_pk_bf16_f32 v113, v228, v232
	v_cvt_pk_bf16_f32 v114, v159, v203
	v_cvt_pk_bf16_f32 v115, v207, v211
	v_cvt_pk_bf16_f32 v116, v215, v219
	v_cvt_pk_bf16_f32 v117, v229, v233
	v_cvt_pk_bf16_f32 v118, v160, v204
	v_cvt_pk_bf16_f32 v119, v208, v212
	v_cvt_pk_bf16_f32 v120, v216, v220
	v_cvt_pk_bf16_f32 v121, v230, v234
	v_add_u32_e32 v132, 128, v130
	v_mad_u64_u32 v[236:237], s[0:1], v132, s69, v[226:227]
	global_load_dwordx3 v[158:160], v[236:237], off nt
	v_add_u32_e32 v132, 129, v130
	v_mad_u64_u32 v[236:237], s[0:1], v132, s69, v[226:227]
	global_load_dwordx3 v[202:204], v[236:237], off nt
	v_add_u32_e32 v132, 130, v130
	v_mad_u64_u32 v[236:237], s[0:1], v132, s69, v[226:227]
	global_load_dwordx3 v[206:208], v[236:237], off nt
	v_add_u32_e32 v132, 131, v130
	v_mad_u64_u32 v[236:237], s[0:1], v132, s69, v[226:227]
	global_load_dwordx3 v[210:212], v[236:237], off nt
	v_add_u32_e32 v132, 132, v130
	v_mad_u64_u32 v[236:237], s[0:1], v132, s69, v[226:227]
	global_load_dwordx3 v[214:216], v[236:237], off nt
	v_add_u32_e32 v132, 133, v130
	v_mad_u64_u32 v[236:237], s[0:1], v132, s69, v[226:227]
	global_load_dwordx3 v[218:220], v[236:237], off nt
	v_add_u32_e32 v132, 134, v130
	v_mad_u64_u32 v[236:237], s[0:1], v132, s69, v[226:227]
	global_load_dwordx3 v[228:230], v[236:237], off nt
	v_add_u32_e32 v132, 135, v130
	v_mad_u64_u32 v[236:237], s[0:1], v132, s69, v[226:227]
	global_load_dwordx3 v[232:234], v[236:237], off nt
	s_nop 1
	v_mfma_f32_16x16x32_bf16 v[18:21], v[142:145], v[110:113], v[18:21]
	v_mfma_f32_16x16x32_bf16 v[6:9], v[142:145], v[114:117], v[6:9]
	v_mfma_f32_16x16x32_bf16 v[2:5], v[142:145], v[118:121], v[2:5]
	s_add_u32 s32, s32, 0x400
	s_addc_u32 s33, s33, 0
	global_load_dwordx4 v[142:145], v134, s[32:33]
	v_mfma_f32_16x16x32_bf16 v[70:73], v[146:149], v[110:113], v[70:73]
	v_mfma_f32_16x16x32_bf16 v[46:49], v[146:149], v[114:117], v[46:49]
	v_mfma_f32_16x16x32_bf16 v[10:13], v[146:149], v[118:121], v[10:13]
	s_add_u32 s32, s32, 0x400
	s_addc_u32 s33, s33, 0
	global_load_dwordx4 v[146:149], v134, s[32:33]
	v_mfma_f32_16x16x32_bf16 v[66:69], v[150:153], v[110:113], v[66:69]
	v_mfma_f32_16x16x32_bf16 v[38:41], v[150:153], v[114:117], v[38:41]
	v_mfma_f32_16x16x32_bf16 v[14:17], v[150:153], v[118:121], v[14:17]
	s_add_u32 s32, s32, 0x400
	s_addc_u32 s33, s33, 0
	global_load_dwordx4 v[150:153], v134, s[32:33]
	s_waitcnt vmcnt(19)
	v_mfma_f32_16x16x32_bf16 v[78:81], v[154:157], v[110:113], v[78:81]
	v_mfma_f32_16x16x32_bf16 v[50:53], v[154:157], v[114:117], v[50:53]
	v_mfma_f32_16x16x32_bf16 v[22:25], v[154:157], v[118:121], v[22:25]
	s_add_u32 s32, s32, 0x400
	s_addc_u32 s33, s33, 0
	global_load_dwordx4 v[154:157], v134, s[32:33]
	s_waitcnt vmcnt(19)
	v_mfma_f32_16x16x32_bf16 v[82:85], v[182:185], v[110:113], v[82:85]
	v_mfma_f32_16x16x32_bf16 v[58:61], v[182:185], v[114:117], v[58:61]
	v_mfma_f32_16x16x32_bf16 v[30:33], v[182:185], v[118:121], v[30:33]
	s_add_u32 s32, s32, 0x400
	s_addc_u32 s33, s33, 0
	global_load_dwordx4 v[182:185], v134, s[32:33]
	s_waitcnt vmcnt(19)
	v_mfma_f32_16x16x32_bf16 v[86:89], v[186:189], v[110:113], v[86:89]
	v_mfma_f32_16x16x32_bf16 v[54:57], v[186:189], v[114:117], v[54:57]
	v_mfma_f32_16x16x32_bf16 v[26:29], v[186:189], v[118:121], v[26:29]
	s_add_u32 s32, s32, 0x400
	s_addc_u32 s33, s33, 0
	global_load_dwordx4 v[186:189], v134, s[32:33]
	s_waitcnt vmcnt(19)
	v_mfma_f32_16x16x32_bf16 v[94:97], v[190:193], v[110:113], v[94:97]
	v_mfma_f32_16x16x32_bf16 v[62:65], v[190:193], v[114:117], v[62:65]
	v_mfma_f32_16x16x32_bf16 v[34:37], v[190:193], v[118:121], v[34:37]
	s_add_u32 s32, s32, 0x400
	s_addc_u32 s33, s33, 0
	global_load_dwordx4 v[190:193], v134, s[32:33]
	s_waitcnt vmcnt(19)
	v_mfma_f32_16x16x32_bf16 v[98:101], v[194:197], v[110:113], v[98:101]
	v_mfma_f32_16x16x32_bf16 v[74:77], v[194:197], v[114:117], v[74:77]
	v_mfma_f32_16x16x32_bf16 v[42:45], v[194:197], v[118:121], v[42:45]
	s_add_u32 s32, s32, 0x400
	s_addc_u32 s33, s33, 0
	global_load_dwordx4 v[194:197], v134, s[32:33]
	s_waitcnt vmcnt(19)
	v_mfma_f32_16x16x32_bf16 v[106:109], v[198:201], v[110:113], v[106:109]
	v_mfma_f32_16x16x32_bf16 v[102:105], v[198:201], v[114:117], v[102:105]
	v_mfma_f32_16x16x32_bf16 v[90:93], v[198:201], v[118:121], v[90:93]
	s_add_u32 s32, s32, 0x400
	s_addc_u32 s33, s33, 0
	global_load_dwordx4 v[198:201], v134, s[32:33]
	s_waitcnt vmcnt(9)
	v_cvt_pk_bf16_f32 v110, v158, v202
	v_cvt_pk_bf16_f32 v111, v206, v210
	v_cvt_pk_bf16_f32 v112, v214, v218
	v_cvt_pk_bf16_f32 v113, v228, v232
	v_cvt_pk_bf16_f32 v114, v159, v203
	v_cvt_pk_bf16_f32 v115, v207, v211
	v_cvt_pk_bf16_f32 v116, v215, v219
	v_cvt_pk_bf16_f32 v117, v229, v233
	v_cvt_pk_bf16_f32 v118, v160, v204
	v_cvt_pk_bf16_f32 v119, v208, v212
	v_cvt_pk_bf16_f32 v120, v216, v220
	v_cvt_pk_bf16_f32 v121, v230, v234
	v_add_u32_e32 v132, 160, v130
	v_mad_u64_u32 v[236:237], s[0:1], v132, s69, v[226:227]
	global_load_dwordx3 v[158:160], v[236:237], off nt
	v_add_u32_e32 v132, 161, v130
	v_mad_u64_u32 v[236:237], s[0:1], v132, s69, v[226:227]
	global_load_dwordx3 v[202:204], v[236:237], off nt
	v_add_u32_e32 v132, 162, v130
	v_mad_u64_u32 v[236:237], s[0:1], v132, s69, v[226:227]
	global_load_dwordx3 v[206:208], v[236:237], off nt
	v_add_u32_e32 v132, 163, v130
	v_mad_u64_u32 v[236:237], s[0:1], v132, s69, v[226:227]
	global_load_dwordx3 v[210:212], v[236:237], off nt
	v_add_u32_e32 v132, 164, v130
	v_mad_u64_u32 v[236:237], s[0:1], v132, s69, v[226:227]
	global_load_dwordx3 v[214:216], v[236:237], off nt
	v_add_u32_e32 v132, 165, v130
	v_mad_u64_u32 v[236:237], s[0:1], v132, s69, v[226:227]
	global_load_dwordx3 v[218:220], v[236:237], off nt
	v_add_u32_e32 v132, 166, v130
	v_mad_u64_u32 v[236:237], s[0:1], v132, s69, v[226:227]
	global_load_dwordx3 v[228:230], v[236:237], off nt
	v_add_u32_e32 v132, 167, v130
	v_mad_u64_u32 v[236:237], s[0:1], v132, s69, v[226:227]
	global_load_dwordx3 v[232:234], v[236:237], off nt
	s_nop 1
	v_mfma_f32_16x16x32_bf16 v[18:21], v[122:125], v[110:113], v[18:21]
	v_mfma_f32_16x16x32_bf16 v[6:9], v[122:125], v[114:117], v[6:9]
	v_mfma_f32_16x16x32_bf16 v[2:5], v[122:125], v[118:121], v[2:5]
	s_add_u32 s32, s32, 0x400
	s_addc_u32 s33, s33, 0
	global_load_dwordx4 v[122:125], v134, s[32:33]
	v_mfma_f32_16x16x32_bf16 v[70:73], v[126:129], v[110:113], v[70:73]
	v_mfma_f32_16x16x32_bf16 v[46:49], v[126:129], v[114:117], v[46:49]
	v_mfma_f32_16x16x32_bf16 v[10:13], v[126:129], v[118:121], v[10:13]
	s_add_u32 s32, s32, 0x400
	s_addc_u32 s33, s33, 0
	global_load_dwordx4 v[126:129], v134, s[32:33]
	v_mfma_f32_16x16x32_bf16 v[66:69], v[138:141], v[110:113], v[66:69]
	v_mfma_f32_16x16x32_bf16 v[38:41], v[138:141], v[114:117], v[38:41]
	v_mfma_f32_16x16x32_bf16 v[14:17], v[138:141], v[118:121], v[14:17]
	s_add_u32 s32, s32, 0x400
	s_addc_u32 s33, s33, 0
	global_load_dwordx4 v[138:141], v134, s[32:33]
	s_waitcnt vmcnt(19)
	v_mfma_f32_16x16x32_bf16 v[78:81], v[142:145], v[110:113], v[78:81]
	v_mfma_f32_16x16x32_bf16 v[50:53], v[142:145], v[114:117], v[50:53]
	v_mfma_f32_16x16x32_bf16 v[22:25], v[142:145], v[118:121], v[22:25]
	s_add_u32 s32, s32, 0x400
	s_addc_u32 s33, s33, 0
	global_load_dwordx4 v[142:145], v134, s[32:33]
	s_waitcnt vmcnt(19)
	v_mfma_f32_16x16x32_bf16 v[82:85], v[146:149], v[110:113], v[82:85]
	v_mfma_f32_16x16x32_bf16 v[58:61], v[146:149], v[114:117], v[58:61]
	v_mfma_f32_16x16x32_bf16 v[30:33], v[146:149], v[118:121], v[30:33]
	s_add_u32 s32, s32, 0x400
	s_addc_u32 s33, s33, 0
	global_load_dwordx4 v[146:149], v134, s[32:33]
	s_waitcnt vmcnt(19)
	v_mfma_f32_16x16x32_bf16 v[86:89], v[150:153], v[110:113], v[86:89]
	v_mfma_f32_16x16x32_bf16 v[54:57], v[150:153], v[114:117], v[54:57]
	v_mfma_f32_16x16x32_bf16 v[26:29], v[150:153], v[118:121], v[26:29]
	s_add_u32 s32, s32, 0x400
	s_addc_u32 s33, s33, 0
	global_load_dwordx4 v[150:153], v134, s[32:33]
	s_waitcnt vmcnt(19)
	v_mfma_f32_16x16x32_bf16 v[94:97], v[154:157], v[110:113], v[94:97]
	v_mfma_f32_16x16x32_bf16 v[62:65], v[154:157], v[114:117], v[62:65]
	v_mfma_f32_16x16x32_bf16 v[34:37], v[154:157], v[118:121], v[34:37]
	s_add_u32 s32, s32, 0x400
	s_addc_u32 s33, s33, 0
	global_load_dwordx4 v[154:157], v134, s[32:33]
	s_waitcnt vmcnt(19)
	v_mfma_f32_16x16x32_bf16 v[98:101], v[182:185], v[110:113], v[98:101]
	v_mfma_f32_16x16x32_bf16 v[74:77], v[182:185], v[114:117], v[74:77]
	v_mfma_f32_16x16x32_bf16 v[42:45], v[182:185], v[118:121], v[42:45]
	s_add_u32 s32, s32, 0x400
	s_addc_u32 s33, s33, 0
	global_load_dwordx4 v[182:185], v134, s[32:33]
	s_waitcnt vmcnt(19)
	v_mfma_f32_16x16x32_bf16 v[106:109], v[186:189], v[110:113], v[106:109]
	v_mfma_f32_16x16x32_bf16 v[102:105], v[186:189], v[114:117], v[102:105]
	v_mfma_f32_16x16x32_bf16 v[90:93], v[186:189], v[118:121], v[90:93]
	s_add_u32 s32, s32, 0x400
	s_addc_u32 s33, s33, 0
	global_load_dwordx4 v[186:189], v134, s[32:33]
	s_waitcnt vmcnt(9)
	v_cvt_pk_bf16_f32 v110, v158, v202
	v_cvt_pk_bf16_f32 v111, v206, v210
	v_cvt_pk_bf16_f32 v112, v214, v218
	v_cvt_pk_bf16_f32 v113, v228, v232
	v_cvt_pk_bf16_f32 v114, v159, v203
	v_cvt_pk_bf16_f32 v115, v207, v211
	v_cvt_pk_bf16_f32 v116, v215, v219
	v_cvt_pk_bf16_f32 v117, v229, v233
	v_cvt_pk_bf16_f32 v118, v160, v204
	v_cvt_pk_bf16_f32 v119, v208, v212
	v_cvt_pk_bf16_f32 v120, v216, v220
	v_cvt_pk_bf16_f32 v121, v230, v234
	v_add_u32_e32 v132, 192, v130
	v_mad_u64_u32 v[236:237], s[0:1], v132, s69, v[226:227]
	global_load_dwordx3 v[158:160], v[236:237], off nt
	v_add_u32_e32 v132, 193, v130
	v_mad_u64_u32 v[236:237], s[0:1], v132, s69, v[226:227]
	global_load_dwordx3 v[202:204], v[236:237], off nt
	v_add_u32_e32 v132, 194, v130
	v_mad_u64_u32 v[236:237], s[0:1], v132, s69, v[226:227]
	global_load_dwordx3 v[206:208], v[236:237], off nt
	v_add_u32_e32 v132, 195, v130
	v_mad_u64_u32 v[236:237], s[0:1], v132, s69, v[226:227]
	global_load_dwordx3 v[210:212], v[236:237], off nt
	v_add_u32_e32 v132, 196, v130
	v_mad_u64_u32 v[236:237], s[0:1], v132, s69, v[226:227]
	global_load_dwordx3 v[214:216], v[236:237], off nt
	v_add_u32_e32 v132, 197, v130
	v_mad_u64_u32 v[236:237], s[0:1], v132, s69, v[226:227]
	global_load_dwordx3 v[218:220], v[236:237], off nt
	v_add_u32_e32 v132, 198, v130
	v_mad_u64_u32 v[236:237], s[0:1], v132, s69, v[226:227]
	global_load_dwordx3 v[228:230], v[236:237], off nt
	v_add_u32_e32 v132, 199, v130
	v_mad_u64_u32 v[236:237], s[0:1], v132, s69, v[226:227]
	global_load_dwordx3 v[232:234], v[236:237], off nt
	s_nop 1
	v_mfma_f32_16x16x32_bf16 v[18:21], v[190:193], v[110:113], v[18:21]
	v_mfma_f32_16x16x32_bf16 v[6:9], v[190:193], v[114:117], v[6:9]
	v_mfma_f32_16x16x32_bf16 v[2:5], v[190:193], v[118:121], v[2:5]
	s_add_u32 s32, s32, 0x400
	s_addc_u32 s33, s33, 0
	global_load_dwordx4 v[190:193], v134, s[32:33]
	v_mfma_f32_16x16x32_bf16 v[70:73], v[194:197], v[110:113], v[70:73]
	v_mfma_f32_16x16x32_bf16 v[46:49], v[194:197], v[114:117], v[46:49]
	v_mfma_f32_16x16x32_bf16 v[10:13], v[194:197], v[118:121], v[10:13]
	s_add_u32 s32, s32, 0x400
	s_addc_u32 s33, s33, 0
	global_load_dwordx4 v[194:197], v134, s[32:33]
	v_mfma_f32_16x16x32_bf16 v[66:69], v[198:201], v[110:113], v[66:69]
	v_mfma_f32_16x16x32_bf16 v[38:41], v[198:201], v[114:117], v[38:41]
	v_mfma_f32_16x16x32_bf16 v[14:17], v[198:201], v[118:121], v[14:17]
	s_add_u32 s32, s32, 0x400
	s_addc_u32 s33, s33, 0
	global_load_dwordx4 v[198:201], v134, s[32:33]
	s_waitcnt vmcnt(19)
	v_mfma_f32_16x16x32_bf16 v[78:81], v[122:125], v[110:113], v[78:81]
	v_mfma_f32_16x16x32_bf16 v[50:53], v[122:125], v[114:117], v[50:53]
	v_mfma_f32_16x16x32_bf16 v[22:25], v[122:125], v[118:121], v[22:25]
	s_add_u32 s32, s32, 0x400
	s_addc_u32 s33, s33, 0
	global_load_dwordx4 v[122:125], v134, s[32:33]
	s_waitcnt vmcnt(19)
	v_mfma_f32_16x16x32_bf16 v[82:85], v[126:129], v[110:113], v[82:85]
	v_mfma_f32_16x16x32_bf16 v[58:61], v[126:129], v[114:117], v[58:61]
	v_mfma_f32_16x16x32_bf16 v[30:33], v[126:129], v[118:121], v[30:33]
	s_add_u32 s32, s32, 0x400
	s_addc_u32 s33, s33, 0
	global_load_dwordx4 v[126:129], v134, s[32:33]
	s_waitcnt vmcnt(19)
	v_mfma_f32_16x16x32_bf16 v[86:89], v[138:141], v[110:113], v[86:89]
	v_mfma_f32_16x16x32_bf16 v[54:57], v[138:141], v[114:117], v[54:57]
	v_mfma_f32_16x16x32_bf16 v[26:29], v[138:141], v[118:121], v[26:29]
	s_add_u32 s32, s32, 0x400
	s_addc_u32 s33, s33, 0
	global_load_dwordx4 v[138:141], v134, s[32:33]
	s_waitcnt vmcnt(19)
	v_mfma_f32_16x16x32_bf16 v[94:97], v[142:145], v[110:113], v[94:97]
	v_mfma_f32_16x16x32_bf16 v[62:65], v[142:145], v[114:117], v[62:65]
	v_mfma_f32_16x16x32_bf16 v[34:37], v[142:145], v[118:121], v[34:37]
	s_add_u32 s32, s32, 0x400
	s_addc_u32 s33, s33, 0
	global_load_dwordx4 v[142:145], v134, s[32:33]
	s_waitcnt vmcnt(19)
	v_mfma_f32_16x16x32_bf16 v[98:101], v[146:149], v[110:113], v[98:101]
	v_mfma_f32_16x16x32_bf16 v[74:77], v[146:149], v[114:117], v[74:77]
	v_mfma_f32_16x16x32_bf16 v[42:45], v[146:149], v[118:121], v[42:45]
	s_add_u32 s32, s32, 0x400
	s_addc_u32 s33, s33, 0
	global_load_dwordx4 v[146:149], v134, s[32:33]
	s_waitcnt vmcnt(19)
	v_mfma_f32_16x16x32_bf16 v[106:109], v[150:153], v[110:113], v[106:109]
	v_mfma_f32_16x16x32_bf16 v[102:105], v[150:153], v[114:117], v[102:105]
	v_mfma_f32_16x16x32_bf16 v[90:93], v[150:153], v[118:121], v[90:93]
	s_add_u32 s32, s32, 0x400
	s_addc_u32 s33, s33, 0
	global_load_dwordx4 v[150:153], v134, s[32:33]
	s_waitcnt vmcnt(9)
	v_cvt_pk_bf16_f32 v110, v158, v202
	v_cvt_pk_bf16_f32 v111, v206, v210
	v_cvt_pk_bf16_f32 v112, v214, v218
	v_cvt_pk_bf16_f32 v113, v228, v232
	v_cvt_pk_bf16_f32 v114, v159, v203
	v_cvt_pk_bf16_f32 v115, v207, v211
	v_cvt_pk_bf16_f32 v116, v215, v219
	v_cvt_pk_bf16_f32 v117, v229, v233
	v_cvt_pk_bf16_f32 v118, v160, v204
	v_cvt_pk_bf16_f32 v119, v208, v212
	v_cvt_pk_bf16_f32 v120, v216, v220
	v_cvt_pk_bf16_f32 v121, v230, v234
	v_add_u32_e32 v132, 224, v130
	v_mad_u64_u32 v[236:237], s[0:1], v132, s69, v[226:227]
	global_load_dwordx3 v[158:160], v[236:237], off nt
	v_add_u32_e32 v132, 225, v130
	v_mad_u64_u32 v[236:237], s[0:1], v132, s69, v[226:227]
	global_load_dwordx3 v[202:204], v[236:237], off nt
	v_add_u32_e32 v132, 226, v130
	v_mad_u64_u32 v[236:237], s[0:1], v132, s69, v[226:227]
	global_load_dwordx3 v[206:208], v[236:237], off nt
	v_add_u32_e32 v132, 227, v130
	v_mad_u64_u32 v[236:237], s[0:1], v132, s69, v[226:227]
	global_load_dwordx3 v[210:212], v[236:237], off nt
	v_add_u32_e32 v132, 228, v130
	v_mad_u64_u32 v[236:237], s[0:1], v132, s69, v[226:227]
	global_load_dwordx3 v[214:216], v[236:237], off nt
	v_add_u32_e32 v132, 229, v130
	v_mad_u64_u32 v[236:237], s[0:1], v132, s69, v[226:227]
	global_load_dwordx3 v[218:220], v[236:237], off nt
	v_add_u32_e32 v132, 230, v130
	v_mad_u64_u32 v[236:237], s[0:1], v132, s69, v[226:227]
	global_load_dwordx3 v[228:230], v[236:237], off nt
	v_add_u32_e32 v132, 231, v130
	v_mad_u64_u32 v[236:237], s[0:1], v132, s69, v[226:227]
	global_load_dwordx3 v[232:234], v[236:237], off nt
	s_nop 1
	v_mfma_f32_16x16x32_bf16 v[18:21], v[154:157], v[110:113], v[18:21]
	v_mfma_f32_16x16x32_bf16 v[6:9], v[154:157], v[114:117], v[6:9]
	v_mfma_f32_16x16x32_bf16 v[2:5], v[154:157], v[118:121], v[2:5]
	s_add_u32 s32, s32, 0x400
	s_addc_u32 s33, s33, 0
	global_load_dwordx4 v[154:157], v134, s[32:33]
	v_mfma_f32_16x16x32_bf16 v[70:73], v[182:185], v[110:113], v[70:73]
	v_mfma_f32_16x16x32_bf16 v[46:49], v[182:185], v[114:117], v[46:49]
	v_mfma_f32_16x16x32_bf16 v[10:13], v[182:185], v[118:121], v[10:13]
	s_add_u32 s32, s32, 0x400
	s_addc_u32 s33, s33, 0
	global_load_dwordx4 v[182:185], v134, s[32:33]
	v_mfma_f32_16x16x32_bf16 v[66:69], v[186:189], v[110:113], v[66:69]
	v_mfma_f32_16x16x32_bf16 v[38:41], v[186:189], v[114:117], v[38:41]
	v_mfma_f32_16x16x32_bf16 v[14:17], v[186:189], v[118:121], v[14:17]
	s_add_u32 s32, s32, 0x400
	s_addc_u32 s33, s33, 0
	global_load_dwordx4 v[186:189], v134, s[32:33]
	s_waitcnt vmcnt(19)
	v_mfma_f32_16x16x32_bf16 v[78:81], v[190:193], v[110:113], v[78:81]
	v_mfma_f32_16x16x32_bf16 v[50:53], v[190:193], v[114:117], v[50:53]
	v_mfma_f32_16x16x32_bf16 v[22:25], v[190:193], v[118:121], v[22:25]
	s_add_u32 s32, s32, 0x400
	s_addc_u32 s33, s33, 0
	global_load_dwordx4 v[190:193], v134, s[32:33]
	s_waitcnt vmcnt(19)
	v_mfma_f32_16x16x32_bf16 v[82:85], v[194:197], v[110:113], v[82:85]
	v_mfma_f32_16x16x32_bf16 v[58:61], v[194:197], v[114:117], v[58:61]
	v_mfma_f32_16x16x32_bf16 v[30:33], v[194:197], v[118:121], v[30:33]
	s_add_u32 s32, s32, 0x400
	s_addc_u32 s33, s33, 0
	global_load_dwordx4 v[194:197], v134, s[32:33]
	s_waitcnt vmcnt(19)
	v_mfma_f32_16x16x32_bf16 v[86:89], v[198:201], v[110:113], v[86:89]
	v_mfma_f32_16x16x32_bf16 v[54:57], v[198:201], v[114:117], v[54:57]
	v_mfma_f32_16x16x32_bf16 v[26:29], v[198:201], v[118:121], v[26:29]
	s_add_u32 s32, s32, 0x400
	s_addc_u32 s33, s33, 0
	global_load_dwordx4 v[198:201], v134, s[32:33]
	s_waitcnt vmcnt(19)
	v_mfma_f32_16x16x32_bf16 v[94:97], v[122:125], v[110:113], v[94:97]
	v_mfma_f32_16x16x32_bf16 v[62:65], v[122:125], v[114:117], v[62:65]
	v_mfma_f32_16x16x32_bf16 v[34:37], v[122:125], v[118:121], v[34:37]
	s_waitcnt vmcnt(18)
	v_mfma_f32_16x16x32_bf16 v[98:101], v[126:129], v[110:113], v[98:101]
	v_mfma_f32_16x16x32_bf16 v[74:77], v[126:129], v[114:117], v[74:77]
	v_mfma_f32_16x16x32_bf16 v[42:45], v[126:129], v[118:121], v[42:45]
	s_waitcnt vmcnt(17)
	v_mfma_f32_16x16x32_bf16 v[106:109], v[138:141], v[110:113], v[106:109]
	v_mfma_f32_16x16x32_bf16 v[102:105], v[138:141], v[114:117], v[102:105]
	v_mfma_f32_16x16x32_bf16 v[90:93], v[138:141], v[118:121], v[90:93]
	s_waitcnt vmcnt(6)
	v_cvt_pk_bf16_f32 v110, v158, v202
	v_cvt_pk_bf16_f32 v111, v206, v210
	v_cvt_pk_bf16_f32 v112, v214, v218
	v_cvt_pk_bf16_f32 v113, v228, v232
	v_cvt_pk_bf16_f32 v114, v159, v203
	v_cvt_pk_bf16_f32 v115, v207, v211
	v_cvt_pk_bf16_f32 v116, v215, v219
	v_cvt_pk_bf16_f32 v117, v229, v233
	v_cvt_pk_bf16_f32 v118, v160, v204
	v_cvt_pk_bf16_f32 v119, v208, v212
	v_cvt_pk_bf16_f32 v120, v216, v220
	v_cvt_pk_bf16_f32 v121, v230, v234
	s_nop 1
	v_mfma_f32_16x16x32_bf16 v[18:21], v[142:145], v[110:113], v[18:21]
	v_mfma_f32_16x16x32_bf16 v[6:9], v[142:145], v[114:117], v[6:9]
	v_mfma_f32_16x16x32_bf16 v[2:5], v[142:145], v[118:121], v[2:5]
	v_mfma_f32_16x16x32_bf16 v[70:73], v[146:149], v[110:113], v[70:73]
	v_mfma_f32_16x16x32_bf16 v[46:49], v[146:149], v[114:117], v[46:49]
	v_mfma_f32_16x16x32_bf16 v[10:13], v[146:149], v[118:121], v[10:13]
	v_mfma_f32_16x16x32_bf16 v[66:69], v[150:153], v[110:113], v[66:69]
	v_mfma_f32_16x16x32_bf16 v[38:41], v[150:153], v[114:117], v[38:41]
	v_mfma_f32_16x16x32_bf16 v[14:17], v[150:153], v[118:121], v[14:17]
	s_waitcnt vmcnt(5)
	v_mfma_f32_16x16x32_bf16 v[78:81], v[154:157], v[110:113], v[78:81]
	v_mfma_f32_16x16x32_bf16 v[50:53], v[154:157], v[114:117], v[50:53]
	v_mfma_f32_16x16x32_bf16 v[22:25], v[154:157], v[118:121], v[22:25]
	s_waitcnt vmcnt(4)
	v_mfma_f32_16x16x32_bf16 v[82:85], v[182:185], v[110:113], v[82:85]
	v_mfma_f32_16x16x32_bf16 v[58:61], v[182:185], v[114:117], v[58:61]
	v_mfma_f32_16x16x32_bf16 v[30:33], v[182:185], v[118:121], v[30:33]
	s_waitcnt vmcnt(3)
	v_mfma_f32_16x16x32_bf16 v[86:89], v[186:189], v[110:113], v[86:89]
	v_mfma_f32_16x16x32_bf16 v[54:57], v[186:189], v[114:117], v[54:57]
	v_mfma_f32_16x16x32_bf16 v[26:29], v[186:189], v[118:121], v[26:29]
	s_waitcnt vmcnt(2)
	v_mfma_f32_16x16x32_bf16 v[94:97], v[190:193], v[110:113], v[94:97]
	v_mfma_f32_16x16x32_bf16 v[62:65], v[190:193], v[114:117], v[62:65]
	v_mfma_f32_16x16x32_bf16 v[34:37], v[190:193], v[118:121], v[34:37]
	s_waitcnt vmcnt(1)
	v_mfma_f32_16x16x32_bf16 v[98:101], v[194:197], v[110:113], v[98:101]
	v_mfma_f32_16x16x32_bf16 v[74:77], v[194:197], v[114:117], v[74:77]
	v_mfma_f32_16x16x32_bf16 v[42:45], v[194:197], v[118:121], v[42:45]
	s_waitcnt vmcnt(0)
	v_mfma_f32_16x16x32_bf16 v[106:109], v[198:201], v[110:113], v[106:109]
	v_mfma_f32_16x16x32_bf16 v[102:105], v[198:201], v[114:117], v[102:105]
	v_mfma_f32_16x16x32_bf16 v[90:93], v[198:201], v[118:121], v[90:93]
	v_lshrrev_b32_e32 v110, 4, v170
	v_lshlrev_b32_e32 v111, 16, v110
	v_lshlrev_b32_e32 v112, 2, v110
	v_or_b32_e32 v112, 0x82, v112
	v_lshlrev_b32_e32 v113, 2, v110
	v_or_b32_e32 v113, 0x80, v113
	v_lshlrev_b32_e32 v114, 2, v110
	v_or_b32_e32 v114, 0x81, v114
	v_or_b32_e32 v132, 0x4000, v111
	v_or_b32_e32 v134, 0x8000, v111
	v_or_b32_e32 v136, 0xc000, v111
	v_or_b32_e32 v138, 0x40000, v111
	v_or_b32_e32 v140, 0x44000, v111
	v_or_b32_e32 v142, 0x48000, v111
	v_or_b32_e32 v144, 0x4c000, v111
	v_or_b32_e32 v146, 0x80000, v111
	v_or_b32_e32 v148, 0x84000, v111
	v_or_b32_e32 v150, 0x88000, v111
	v_or_b32_e32 v152, 0x8c000, v111
	v_or_b32_e32 v154, 0xc0000, v111
	v_or_b32_e32 v156, 0xc4000, v111
	v_or_b32_e32 v158, 0xc8000, v111
	v_or_b32_e32 v160, 0xcc000, v111
	v_or_b32_e32 v182, 0x100000, v111
	v_or_b32_e32 v184, 0x104000, v111
	v_or_b32_e32 v186, 0x108000, v111
	v_or_b32_e32 v188, 0x10c000, v111
	v_or_b32_e32 v190, 0x140000, v111
	v_or_b32_e32 v192, 0x144000, v111
	v_or_b32_e32 v194, 0x148000, v111
	v_or_b32_e32 v196, 0x14c000, v111
	v_or_b32_e32 v198, 0x180000, v111
	v_or_b32_e32 v200, 0x184000, v111
	v_or_b32_e32 v202, 0x188000, v111
	v_or_b32_e32 v204, 0x18c000, v111
	v_or_b32_e32 v206, 0x1c0000, v111
	v_or_b32_e32 v208, 0x1c4000, v111
	v_or_b32_e32 v210, 0x1c8000, v111
	v_or_b32_e32 v212, 0x1cc000, v111
	v_lshlrev_b32_e32 v214, 2, v111
	v_add_u32_e32 v189, 0xffff7000, v137
	v_add_u32_e32 v191, 0xffff7100, v137
	v_add_u32_e32 v193, 0xffff7200, v137
	v_add_u32_e32 v195, 0xffff7300, v137
	v_add_u32_e32 v197, 0xffff7400, v137
	v_add_u32_e32 v199, 0xffff7500, v137
	v_add_u32_e32 v201, 0xffff7600, v137
	v_add_u32_e32 v203, 0xffff7700, v137
	v_add_u32_e32 v205, 0xffff7800, v137
	v_add_u32_e32 v207, 0xffff7900, v137
	v_add_u32_e32 v209, 0xffff7a00, v137
	v_add_u32_e32 v211, 0xffff7b00, v137
	v_add_u32_e32 v213, 0xffff7c00, v137
	v_add_u32_e32 v217, 0xffff7d00, v137
	v_add_u32_e32 v219, 0xffff7e00, v137
	v_add_u32_e32 v221, 0xffff7f00, v137
	v_add_u32_e32 v171, 0xffff8000, v137
	v_add_u32_e32 v247, 0xffff8100, v137
	v_add_u32_e32 v183, 0xffff8200, v137
	v_add_u32_e32 v185, 0xffff8300, v137
	v_add_u32_e32 v187, 0xffff8400, v137
	v_add_u32_e32 v251, 0xffff8500, v137
	v_add_u32_e32 v252, 0xffff8600, v137
	v_add_u32_e32 v253, 0xffff8700, v137
	v_add_u32_e32 v254, 0xffff8800, v137
	v_add_u32_e32 v139, 0xffff8900, v137
	v_add_u32_e32 v141, 0xffff8a00, v137
	v_add_u32_e32 v143, 0xffff8b00, v137
	v_add_u32_e32 v145, 0xffff8c00, v137
	v_add_u32_e32 v147, 0xffff8d00, v137
	v_add_u32_e32 v149, 0xffff8e00, v137
	v_add_u32_e32 v151, 0xffff8f00, v137
	v_add_u32_e32 v153, 0xffff9000, v137
	v_add_u32_e32 v155, 0xffff9100, v137
	v_add_u32_e32 v157, 0xffff9200, v137
	v_add_u32_e32 v159, 0xffff9300, v137
	v_lshlrev_b32_e32 v216, 14, v113
	v_lshlrev_b32_e32 v218, 14, v114
	v_lshlrev_b32_e32 v220, 14, v112
	s_and_b64 vcc, exec, s[10:11]
	s_cbranch_vccz .LBB0_85
	v_add_u32_e32 v110, 0xfffe5000, v137
	ds_write_b32 v110, v18
	v_add_u32_e32 v110, 0xfffe5100, v137
	ds_write_b32 v110, v19
	v_add_u32_e32 v110, 0xfffe5200, v137
	ds_write_b32 v110, v20
	v_add_u32_e32 v110, 0xfffe5300, v137
	ds_write_b32 v110, v21
	v_add_u32_e32 v110, 0xfffe5400, v137
	ds_write_b32 v110, v6
	v_add_u32_e32 v110, 0xfffe5500, v137
	ds_write_b32 v110, v7
	v_add_u32_e32 v110, 0xfffe5600, v137
	ds_write_b32 v110, v8
	v_add_u32_e32 v110, 0xfffe5700, v137
	ds_write_b32 v110, v9
	v_add_u32_e32 v110, 0xfffe5800, v137
	ds_write_b32 v110, v2
	v_add_u32_e32 v110, 0xfffe5900, v137
	ds_write_b32 v110, v3
	v_add_u32_e32 v110, 0xfffe5a00, v137
	ds_write_b32 v110, v4
	v_add_u32_e32 v110, 0xfffe5b00, v137
	ds_write_b32 v110, v5
	v_add_u32_e32 v110, 0xfffe5c00, v137
	ds_write_b32 v110, v70
	v_add_u32_e32 v110, 0xfffe5d00, v137
	ds_write_b32 v110, v71
	v_add_u32_e32 v110, 0xfffe5e00, v137
	ds_write_b32 v110, v72
	v_add_u32_e32 v110, 0xfffe5f00, v137
	ds_write_b32 v110, v73
	v_add_u32_e32 v110, 0xfffe6000, v137
	ds_write_b32 v110, v46
	v_add_u32_e32 v110, 0xfffe6100, v137
	ds_write_b32 v110, v47
	v_add_u32_e32 v110, 0xfffe6200, v137
	ds_write_b32 v110, v48
	v_add_u32_e32 v110, 0xfffe6300, v137
	ds_write_b32 v110, v49
	v_add_u32_e32 v110, 0xfffe6400, v137
	ds_write_b32 v110, v10
	v_add_u32_e32 v110, 0xfffe6500, v137
	ds_write_b32 v110, v11
	v_add_u32_e32 v110, 0xfffe6600, v137
	ds_write_b32 v110, v12
	v_add_u32_e32 v110, 0xfffe6700, v137
	ds_write_b32 v110, v13
	v_add_u32_e32 v110, 0xfffe6800, v137
	ds_write_b32 v110, v66
	v_add_u32_e32 v110, 0xfffe6900, v137
	ds_write_b32 v110, v67
	v_add_u32_e32 v110, 0xfffe6a00, v137
	ds_write_b32 v110, v68
	v_add_u32_e32 v110, 0xfffe6b00, v137
	ds_write_b32 v110, v69
	v_add_u32_e32 v110, 0xfffe6c00, v137
	ds_write_b32 v110, v38
	v_add_u32_e32 v110, 0xfffe6d00, v137
	ds_write_b32 v110, v39
	v_add_u32_e32 v110, 0xfffe6e00, v137
	ds_write_b32 v110, v40
	v_add_u32_e32 v110, 0xfffe6f00, v137
	ds_write_b32 v110, v41
	v_add_u32_e32 v110, 0xfffe7000, v137
	ds_write_b32 v110, v14
	v_add_u32_e32 v110, 0xfffe7100, v137
	ds_write_b32 v110, v15
	v_add_u32_e32 v110, 0xfffe7200, v137
	ds_write_b32 v110, v16
	v_add_u32_e32 v110, 0xfffe7300, v137
	ds_write_b32 v110, v17
	v_add_u32_e32 v110, 0xfffe7400, v137
	ds_write_b32 v110, v78
	v_add_u32_e32 v110, 0xfffe7500, v137
	ds_write_b32 v110, v79
	v_add_u32_e32 v110, 0xfffe7600, v137
	ds_write_b32 v110, v80
	v_add_u32_e32 v110, 0xfffe7700, v137
	ds_write_b32 v110, v81
	v_add_u32_e32 v110, 0xfffe7800, v137
	ds_write_b32 v110, v50
	v_add_u32_e32 v110, 0xfffe7900, v137
	ds_write_b32 v110, v51
	v_add_u32_e32 v110, 0xfffe7a00, v137
	ds_write_b32 v110, v52
	v_add_u32_e32 v110, 0xfffe7b00, v137
	ds_write_b32 v110, v53
	v_add_u32_e32 v110, 0xfffe7c00, v137
	ds_write_b32 v110, v22
	v_add_u32_e32 v110, 0xfffe7d00, v137
	ds_write_b32 v110, v23
	v_add_u32_e32 v110, 0xfffe7e00, v137
	ds_write_b32 v110, v24
	v_add_u32_e32 v110, 0xfffe7f00, v137
	ds_write_b32 v110, v25
	v_add_u32_e32 v110, 0xfffe8000, v137
	ds_write_b32 v110, v82
	v_add_u32_e32 v110, 0xfffe8100, v137
	ds_write_b32 v110, v83
	v_add_u32_e32 v110, 0xfffe8200, v137
	ds_write_b32 v110, v84
	v_add_u32_e32 v110, 0xfffe8300, v137
	ds_write_b32 v110, v85
	v_add_u32_e32 v110, 0xfffe8400, v137
	ds_write_b32 v110, v58
	v_add_u32_e32 v110, 0xfffe8500, v137
	ds_write_b32 v110, v59
	v_add_u32_e32 v110, 0xfffe8600, v137
	ds_write_b32 v110, v60
	v_add_u32_e32 v110, 0xfffe8700, v137
	ds_write_b32 v110, v61
	v_add_u32_e32 v110, 0xfffe8800, v137
	ds_write_b32 v110, v30
	v_add_u32_e32 v110, 0xfffe8900, v137
	ds_write_b32 v110, v31
	v_add_u32_e32 v110, 0xfffe8a00, v137
	ds_write_b32 v110, v32
	v_add_u32_e32 v110, 0xfffe8b00, v137
	ds_write_b32 v110, v33
	v_add_u32_e32 v110, 0xfffe8c00, v137
	ds_write_b32 v110, v86
	v_add_u32_e32 v110, 0xfffe8d00, v137
	ds_write_b32 v110, v87
	v_add_u32_e32 v110, 0xfffe8e00, v137
	ds_write_b32 v110, v88
	v_add_u32_e32 v110, 0xfffe8f00, v137
	ds_write_b32 v110, v89
	v_add_u32_e32 v110, 0xfffe9000, v137
	ds_write_b32 v110, v54
	v_add_u32_e32 v110, 0xfffe9100, v137
	ds_write_b32 v110, v55
	v_add_u32_e32 v110, 0xfffe9200, v137
	ds_write_b32 v110, v56
	v_add_u32_e32 v110, 0xfffe9300, v137
	ds_write_b32 v110, v57
	v_add_u32_e32 v110, 0xfffe9400, v137
	ds_write_b32 v110, v26
	v_add_u32_e32 v110, 0xfffe9500, v137
	ds_write_b32 v110, v27
	v_add_u32_e32 v110, 0xfffe9600, v137
	ds_write_b32 v110, v28
	v_add_u32_e32 v110, 0xfffe9700, v137
	ds_write_b32 v110, v29
	v_add_u32_e32 v110, 0xfffe9800, v137
	ds_write_b32 v110, v94
	v_add_u32_e32 v110, 0xfffe9900, v137
	ds_write_b32 v110, v95
	v_add_u32_e32 v110, 0xfffe9a00, v137
	ds_write_b32 v110, v96
	v_add_u32_e32 v110, 0xfffe9b00, v137
	ds_write_b32 v110, v97
	v_add_u32_e32 v110, 0xfffe9c00, v137
	ds_write_b32 v110, v62
	v_add_u32_e32 v110, 0xfffe9d00, v137
	ds_write_b32 v110, v63
	v_add_u32_e32 v110, 0xfffe9e00, v137
	ds_write_b32 v110, v64
	v_add_u32_e32 v110, 0xfffe9f00, v137
	ds_write_b32 v110, v65
	v_add_u32_e32 v110, 0xfffea000, v137
	ds_write_b32 v110, v34
	v_add_u32_e32 v110, 0xfffea100, v137
	ds_write_b32 v110, v35
	v_add_u32_e32 v110, 0xfffea200, v137
	ds_write_b32 v110, v36
	v_add_u32_e32 v110, 0xfffea300, v137
	ds_write_b32 v110, v37
	v_add_u32_e32 v110, 0xfffea400, v137
	ds_write_b32 v110, v98
	v_add_u32_e32 v110, 0xfffea500, v137
	ds_write_b32 v110, v99
	v_add_u32_e32 v110, 0xfffea600, v137
	ds_write_b32 v110, v100
	v_add_u32_e32 v110, 0xfffea700, v137
	ds_write_b32 v110, v101
	v_add_u32_e32 v110, 0xfffea800, v137
	ds_write_b32 v110, v74
	v_add_u32_e32 v110, 0xfffea900, v137
	ds_write_b32 v110, v75
	v_add_u32_e32 v110, 0xfffeaa00, v137
	ds_write_b32 v110, v76
	v_add_u32_e32 v110, 0xfffeab00, v137
	ds_write_b32 v110, v77
	v_add_u32_e32 v110, 0xfffeac00, v137
	ds_write_b32 v110, v42
	v_add_u32_e32 v110, 0xfffead00, v137
	ds_write_b32 v110, v43
	v_add_u32_e32 v110, 0xfffeae00, v137
	ds_write_b32 v110, v44
	v_add_u32_e32 v110, 0xfffeaf00, v137
	ds_write_b32 v110, v45
	v_add_u32_e32 v110, 0xfffeb000, v137
	ds_write_b32 v110, v106
	v_add_u32_e32 v110, 0xfffeb100, v137
	ds_write_b32 v110, v107
	v_add_u32_e32 v110, 0xfffeb200, v137
	ds_write_b32 v110, v108
	v_add_u32_e32 v110, 0xfffeb300, v137
	ds_write_b32 v110, v109
	v_add_u32_e32 v110, 0xfffeb400, v137
	ds_write_b32 v110, v102
	v_add_u32_e32 v110, 0xfffeb500, v137
	ds_write_b32 v110, v103
	v_add_u32_e32 v110, 0xfffeb600, v137
	ds_write_b32 v110, v104
	v_add_u32_e32 v110, 0xfffeb700, v137
	ds_write_b32 v110, v105
	v_add_u32_e32 v110, 0xfffeb800, v137
	ds_write_b32 v110, v90
	v_add_u32_e32 v110, 0xfffeb900, v137
	ds_write_b32 v110, v91
	v_add_u32_e32 v110, 0xfffeba00, v137
	ds_write_b32 v110, v92
	v_add_u32_e32 v110, 0xfffebb00, v137
	ds_write_b32 v110, v93
